# NSA pass A: all compressed-K tiles of the work item requested up front into idle registers, loop unrolled by tile (no per-step load latency)
# baseline (speedup 1.0000x reference)
.LBB0_1929:
	s_or_b64 exec, exec, s[22:23]
	ds_write_b32 v175, v105 offset:8448
	ds_write_b32 v175, v105 offset:9472
	ds_write_b32 v175, v105 offset:10496
	ds_write_b32 v175, v105 offset:11520
	ds_write_b32 v175, v105 offset:12544
	ds_write_b32 v175, v105 offset:13568
	ds_write_b32 v175, v105 offset:14592
	ds_write_b32 v175, v105 offset:15616
	ds_write_b32 v175, v105 offset:16640
	s_lshl_b32 s20, s99, 1
	s_and_b32 s70, s20, -16
	s_sub_i32 s67, 0x1ff0, s70
	v_add_u32_e32 v132, s67, v103
	s_lshl_b32 s20, s99, 12
	s_and_b32 s54, s20, 0x6000
	s_mov_b32 s55, s39
	v_ashrrev_i32_e32 v133, 31, v132
	s_lshl_b32 s20, s99, 3
	v_lshl_add_u64 v[2:3], v[132:133], 0, s[54:55]
	s_and_b32 s55, s20, 8
	v_lshlrev_b64 v[4:5], 11, v[2:3]
	v_or_b32_e32 v6, s55, v102
	v_lshl_add_u64 v[4:5], s[42:43], 0, v[4:5]
	v_lshlrev_b32_e32 v104, 7, v6
	v_mad_u64_u32 v[6:7], s[20:21], v2, s49, v[124:125]
	v_lshl_add_u64 v[4:5], v[4:5], 0, v[104:105]
	v_mad_i32_i24 v7, v3, s49, v7
	s_lshl_b32 s20, s55, 2
	s_mov_b32 s21, s39
	v_lshl_add_u64 v[4:5], v[4:5], 0, v[122:123]
	v_lshl_add_u64 v[2:3], v[6:7], 0, s[20:21]
	global_load_dwordx4 v[66:69], v[4:5], off offset:32
	global_load_dwordx4 v[70:73], v[4:5], off offset:64
	global_load_dwordx4 v[74:77], v[4:5], off offset:96
	v_lshl_add_u64 v[130:131], v[2:3], 0, v[126:127]
	global_load_dwordx4 v[78:81], v[4:5], off
	global_load_dword v133, v[130:131], off
	global_load_dword v104, v[130:131], off offset:128
	s_and_b32 s20, s99, 7
	s_lshl_b32 s38, s20, 16
	s_lshr_b32 s20, s30, 4
	s_add_i32 s20, s20, 63
	s_lshr_b32 s20, s20, 6
	s_sub_i32 s28, 0, s20
	s_lshr_b32 s20, s67, 4
	s_and_b32 s71, s99, 7
	s_lshl_b32 s80, s71, 20
	v_readlane_b32 s76, v231, 14
	v_readlane_b32 s77, v231, 10
	s_add_u32 s76, s76, s80
	s_addc_u32 s77, s77, 0
	s_add_u32 s78, s52, s80
	s_addc_u32 s79, s53, 0
	v_add_u32_e32 v240, v128, v106
	global_load_dwordx4 v[240:243], v240, s[76:77]
	v_add_u32_e32 v244, v128, v106
	global_load_dwordx4 v[244:247], v244, s[78:79]
	v_add_u32_e32 v248, v128, v108
	global_load_dwordx4 v[248:251], v248, s[76:77]
	v_add_u32_e32 v252, v128, v108
	global_load_dwordx4 v[252:255], v252, s[78:79]
	s_add_i32 s20, s20, 63
	s_lshr_b32 s29, s20, 6
	s_lshl_b32 s30, s71, 16
	s_add_u32 s22, s26, s30
	s_addc_u32 s23, s27, 0
	s_cmpk_lg_i32 s70, 0x1ff0
	s_cselect_b64 s[24:25], -1, 0
	s_cmpk_eq_i32 s70, 0x1ff0
	v_mov_b32_e32 v54, 0
	s_cbranch_scc1 .LBB0_1942
	v_mov_b32_e32 v129, v105
	v_lshl_add_u64 v[2:3], s[22:23], 0, v[128:129]
	v_lshl_add_u64 v[4:5], v[2:3], 0, v[106:107]
	v_lshl_add_u64 v[6:7], v[2:3], 0, v[108:109]
	global_load_dwordx4 v[34:37], v[4:5], off
	global_load_dwordx4 v[38:41], v[6:7], off
	v_lshl_add_u64 v[2:3], v[2:3], 0, s[40:41]
	v_lshl_add_u64 v[58:59], v[2:3], 0, v[106:107]
	global_load_dwordx4 v[58:61], v[58:59], off
	v_lshl_add_u64 v[62:63], v[2:3], 0, v[108:109]
	global_load_dwordx4 v[62:65], v[62:63], off
	v_lshl_add_u64 v[2:3], v[2:3], 0, s[40:41]
	v_lshl_add_u64 v[82:83], v[2:3], 0, v[106:107]
	global_load_dwordx4 v[82:85], v[82:83], off
	v_lshl_add_u64 v[86:87], v[2:3], 0, v[108:109]
	global_load_dwordx4 v[86:89], v[86:87], off
	v_lshl_add_u64 v[2:3], v[2:3], 0, s[40:41]
	v_lshl_add_u64 v[90:91], v[2:3], 0, v[106:107]
	global_load_dwordx4 v[90:93], v[90:91], off
	v_lshl_add_u64 v[94:95], v[2:3], 0, v[108:109]
	global_load_dwordx4 v[94:97], v[94:95], off
	v_lshl_add_u64 v[2:3], v[2:3], 0, s[40:41]
	v_lshl_add_u64 v[134:135], v[2:3], 0, v[106:107]
	global_load_dwordx4 v[134:137], v[134:135], off
	v_lshl_add_u64 v[138:139], v[2:3], 0, v[108:109]
	global_load_dwordx4 v[138:141], v[138:139], off
	v_lshl_add_u64 v[2:3], v[2:3], 0, s[40:41]
	v_lshl_add_u64 v[142:143], v[2:3], 0, v[106:107]
	global_load_dwordx4 v[142:145], v[142:143], off
	v_lshl_add_u64 v[146:147], v[2:3], 0, v[108:109]
	global_load_dwordx4 v[146:149], v[146:147], off
	v_lshl_add_u64 v[2:3], v[2:3], 0, s[40:41]
	v_lshl_add_u64 v[216:217], v[2:3], 0, v[106:107]
	global_load_dwordx4 v[216:219], v[216:217], off
	v_lshl_add_u64 v[220:221], v[2:3], 0, v[108:109]
	global_load_dwordx4 v[220:223], v[220:221], off
	v_lshl_add_u64 v[2:3], v[2:3], 0, s[40:41]
	v_lshl_add_u64 v[224:225], v[2:3], 0, v[106:107]
	global_load_dwordx4 v[224:227], v[224:225], off
	v_lshl_add_u64 v[234:235], v[2:3], 0, v[108:109]
	global_load_dwordx4 v[234:237], v[234:235], off
	s_waitcnt vmcnt(15)
	ds_write_b128 v153, v[34:37]
	s_waitcnt vmcnt(14)
	ds_write_b128 v155, v[38:41]

.Lapa0_1934:
	s_add_i32 s20, s31, -2
	s_and_b32 s20, s20, 1
	s_add_i32 s21, s31, -1
	s_cmp_ge_u32 s21, s29
	s_cbranch_scc1 .Lapa0_1936
	s_xor_b32 s21, s20, 1
	s_mulk_i32 s21, 0x4800
	v_or_b32_e32 v2, s21, v111
	v_lshl_add_u32 v3, v154, 1, v2
	v_lshl_add_u32 v2, v152, 1, v2
	s_waitcnt vmcnt(13)
	ds_write_b128 v2, v[58:61]
	s_waitcnt vmcnt(12)
	ds_write_b128 v3, v[62:65]
.Lapa0_1936:
	s_cmp_ge_u32 s31, s29
	s_cbranch_scc1 .Lapa0_1938
.Lapa0_1938:
	s_mulk_i32 s20, 0x4800
	v_add_u32_e32 v50, s20, v156
	ds_read_b128 v[2:5], v50
	ds_read_b128 v[6:9], v50 offset:32
	s_waitcnt lgkmcnt(1)
	v_mfma_f32_32x32x16_bf16 v[18:33], v[2:5], v[78:81], 0
	s_waitcnt lgkmcnt(0)
	v_mfma_f32_32x32x16_bf16 v[18:33], v[6:9], v[66:69], v[18:33]
	ds_read_b128 v[2:5], v50 offset:64
	ds_read_b128 v[6:9], v50 offset:96
	s_waitcnt lgkmcnt(1)
	v_mfma_f32_32x32x16_bf16 v[18:33], v[2:5], v[70:73], v[18:33]
	ds_read_b128 v[2:5], v50 offset:4608
	ds_read_b128 v[46:49], v50 offset:4640
	s_waitcnt lgkmcnt(2)
	v_mfma_f32_32x32x16_bf16 v[18:33], v[6:9], v[74:77], v[18:33]
	s_waitcnt lgkmcnt(1)
	v_mfma_f32_32x32x16_bf16 v[2:17], v[2:5], v[78:81], 0
	s_waitcnt lgkmcnt(0)
	v_mfma_f32_32x32x16_bf16 v[2:17], v[46:49], v[66:69], v[2:17]
	ds_read_b128 v[46:49], v50 offset:4672
	ds_read_b128 v[50:53], v50 offset:4704
	s_waitcnt lgkmcnt(1)
	v_mfma_f32_32x32x16_bf16 v[2:17], v[46:49], v[70:73], v[2:17]
	s_waitcnt lgkmcnt(0)
	v_mfma_f32_32x32x16_bf16 v[2:17], v[50:53], v[74:77], v[2:17]
	v_cmp_lt_i32_e32 vcc, 26, v55
	s_nop 0
	v_fma_f32 v18, v18, s48, v100
	v_fma_f32 v19, v19, s48, v101
	v_fma_f32 v20, v20, s48, v100
	v_fma_f32 v21, v21, s48, v101
	v_pk_fma_f32 v[22:23], v[22:23], s[48:49], v[100:101] op_sel_hi:[1,0,1]
	v_pk_fma_f32 v[24:25], v[24:25], s[48:49], v[100:101] op_sel_hi:[1,0,1]
	v_pk_fma_f32 v[26:27], v[26:27], s[48:49], v[100:101] op_sel_hi:[1,0,1]
	v_pk_fma_f32 v[28:29], v[28:29], s[48:49], v[100:101] op_sel_hi:[1,0,1]
	v_pk_fma_f32 v[30:31], v[30:31], s[48:49], v[100:101] op_sel_hi:[1,0,1]
	s_cmp_eq_u64 vcc, exec
	v_pk_fma_f32 v[32:33], v[32:33], s[48:49], v[100:101] op_sel_hi:[1,0,1]
	s_cbranch_scc1 .Lapa0_1940
	v_cmp_lt_i32_e64 s[20:21], -1, v55
	v_cndmask_b32_e32 v33, v213, v33, vcc
	s_nop 0
	v_cndmask_b32_e64 v18, v213, v18, s[20:21]
	v_cmp_lt_i32_e64 s[20:21], 0, v55
	s_nop 1
	v_cndmask_b32_e64 v19, v213, v19, s[20:21]
	v_cmp_lt_i32_e64 s[20:21], 1, v55
	s_nop 1
	v_cndmask_b32_e64 v20, v213, v20, s[20:21]
	v_cmp_lt_i32_e64 s[20:21], 2, v55
	s_nop 1
	v_cndmask_b32_e64 v21, v213, v21, s[20:21]
	v_cmp_lt_i32_e64 s[20:21], 7, v55
	s_nop 1
	v_cndmask_b32_e64 v22, v213, v22, s[20:21]
	v_cmp_lt_i32_e64 s[20:21], 8, v55
	s_nop 1
	v_cndmask_b32_e64 v23, v213, v23, s[20:21]
	v_cmp_lt_i32_e64 s[20:21], 9, v55
	s_nop 1
	v_cndmask_b32_e64 v24, v213, v24, s[20:21]
	v_cmp_lt_i32_e64 s[20:21], 10, v55
	s_nop 1
	v_cndmask_b32_e64 v25, v213, v25, s[20:21]
	v_cmp_lt_i32_e64 s[20:21], 15, v55
	s_nop 1
	v_cndmask_b32_e64 v26, v213, v26, s[20:21]
	v_cmp_lt_i32_e64 s[20:21], 16, v55
	s_nop 1
	v_cndmask_b32_e64 v27, v213, v27, s[20:21]
	v_cmp_lt_i32_e64 s[20:21], 17, v55
	s_nop 1
	v_cndmask_b32_e64 v28, v213, v28, s[20:21]
	v_cmp_lt_i32_e64 s[20:21], 18, v55
	s_nop 1
	v_cndmask_b32_e64 v29, v213, v29, s[20:21]
	v_cmp_lt_i32_e64 s[20:21], 23, v55
	s_nop 1
	v_cndmask_b32_e64 v30, v213, v30, s[20:21]
	v_cmp_lt_i32_e64 s[20:21], 24, v55
	s_nop 1
	v_cndmask_b32_e64 v31, v213, v31, s[20:21]
	v_cmp_lt_i32_e64 s[20:21], 25, v55
	s_nop 1
	v_cndmask_b32_e64 v32, v213, v32, s[20:21]
.Lapa0_1940:
	v_subrev_u32_e32 v56, 32, v55
	v_cmp_lt_i32_e32 vcc, 26, v56
	v_pk_fma_f32 v[52:53], v[2:3], s[48:49], v[100:101] op_sel_hi:[1,0,1]
	v_pk_fma_f32 v[50:51], v[4:5], s[48:49], v[100:101] op_sel_hi:[1,0,1]
	v_pk_fma_f32 v[48:49], v[6:7], s[48:49], v[100:101] op_sel_hi:[1,0,1]
	v_pk_fma_f32 v[46:47], v[8:9], s[48:49], v[100:101] op_sel_hi:[1,0,1]
	v_pk_fma_f32 v[8:9], v[10:11], s[48:49], v[100:101] op_sel_hi:[1,0,1]
	v_pk_fma_f32 v[6:7], v[12:13], s[48:49], v[100:101] op_sel_hi:[1,0,1]
	v_pk_fma_f32 v[2:3], v[14:15], s[48:49], v[100:101] op_sel_hi:[1,0,1]
	s_cmp_eq_u64 vcc, exec
	v_pk_fma_f32 v[4:5], v[16:17], s[48:49], v[100:101] op_sel_hi:[1,0,1]
	s_cbranch_scc1 .Lapa0_1933
	v_cmp_lt_i32_e64 s[20:21], -1, v56
	v_cndmask_b32_e32 v5, v213, v5, vcc
	s_nop 0
	v_cndmask_b32_e64 v52, v213, v52, s[20:21]
	v_cmp_lt_i32_e64 s[20:21], 0, v56
	s_nop 1
	v_cndmask_b32_e64 v53, v213, v53, s[20:21]
	v_cmp_lt_i32_e64 s[20:21], 1, v56
	s_nop 1
	v_cndmask_b32_e64 v50, v213, v50, s[20:21]
	v_cmp_lt_i32_e64 s[20:21], 2, v56
	s_nop 1
	v_cndmask_b32_e64 v51, v213, v51, s[20:21]
	v_cmp_lt_i32_e64 s[20:21], 7, v56
	s_nop 1
	v_cndmask_b32_e64 v48, v213, v48, s[20:21]
	v_cmp_lt_i32_e64 s[20:21], 8, v56
	s_nop 1
	v_cndmask_b32_e64 v49, v213, v49, s[20:21]
	v_cmp_lt_i32_e64 s[20:21], 9, v56
	s_nop 1
	v_cndmask_b32_e64 v46, v213, v46, s[20:21]
	v_cmp_lt_i32_e64 s[20:21], 10, v56
	s_nop 1
	v_cndmask_b32_e64 v47, v213, v47, s[20:21]
	v_cmp_lt_i32_e64 s[20:21], 15, v56
	s_nop 1
	v_cndmask_b32_e64 v8, v213, v8, s[20:21]
	v_cmp_lt_i32_e64 s[20:21], 16, v56
	s_nop 1
	v_cndmask_b32_e64 v9, v213, v9, s[20:21]
	v_cmp_lt_i32_e64 s[20:21], 17, v56
	s_nop 1
	v_cndmask_b32_e64 v6, v213, v6, s[20:21]
	v_cmp_lt_i32_e64 s[20:21], 18, v56
	s_nop 1
	v_cndmask_b32_e64 v7, v213, v7, s[20:21]
	v_cmp_lt_i32_e64 s[20:21], 23, v56
	s_nop 1
	v_cndmask_b32_e64 v2, v213, v2, s[20:21]
	v_cmp_lt_i32_e64 s[20:21], 24, v56
	s_nop 1
	v_cndmask_b32_e64 v3, v213, v3, s[20:21]
	v_cmp_lt_i32_e64 s[20:21], 25, v56
	s_nop 1
	v_cndmask_b32_e64 v4, v213, v4, s[20:21]
	s_branch .Lapa0_1933
.Lapa0_1933:
	v_exp_f32_e32 v10, v18
	v_exp_f32_e32 v11, v19
	v_exp_f32_e32 v12, v20
	v_exp_f32_e32 v13, v21
	v_exp_f32_e32 v14, v22
	v_add_f32_e32 v10, 0, v10
	v_exp_f32_e32 v15, v23
	v_add_f32_e32 v10, v11, v10
	v_exp_f32_e32 v16, v24
	v_add_f32_e32 v10, v12, v10
	v_exp_f32_e32 v17, v25
	v_add_f32_e32 v10, v13, v10
	v_exp_f32_e32 v18, v26
	v_add_f32_e32 v10, v14, v10
	v_exp_f32_e32 v19, v27
	v_add_f32_e32 v10, v15, v10
	v_exp_f32_e32 v20, v28
	v_add_f32_e32 v10, v16, v10
	v_exp_f32_e32 v21, v29
	v_add_f32_e32 v10, v17, v10
	v_exp_f32_e32 v22, v30
	v_add_f32_e32 v10, v18, v10
	v_exp_f32_e32 v23, v31
	v_add_f32_e32 v10, v19, v10
	v_exp_f32_e32 v24, v32
	v_add_f32_e32 v10, v20, v10
	v_exp_f32_e32 v25, v33
	v_add_f32_e32 v10, v21, v10
	v_add_f32_e32 v10, v22, v10
	v_exp_f32_e32 v11, v52
	v_add_f32_e32 v10, v23, v10
	v_exp_f32_e32 v12, v53
	v_add_f32_e32 v10, v24, v10
	v_exp_f32_e32 v13, v50
	v_add_f32_e32 v10, v25, v10
	v_exp_f32_e32 v14, v51
	v_add_f32_e32 v10, v10, v11
	v_exp_f32_e32 v11, v48
	v_add_f32_e32 v10, v12, v10
	v_exp_f32_e32 v12, v49
	v_add_f32_e32 v10, v13, v10
	v_exp_f32_e32 v13, v46
	v_add_f32_e32 v10, v14, v10
	v_exp_f32_e32 v14, v47
	v_add_f32_e32 v10, v11, v10
	v_exp_f32_e32 v8, v8
	v_add_f32_e32 v10, v12, v10
	v_exp_f32_e32 v9, v9
	v_add_f32_e32 v10, v13, v10
	v_exp_f32_e32 v6, v6
	v_add_f32_e32 v10, v14, v10
	v_exp_f32_e32 v7, v7
	v_add_f32_e32 v8, v8, v10
	v_exp_f32_e32 v2, v2
	v_add_f32_e32 v8, v9, v8
	v_exp_f32_e32 v3, v3
	v_add_f32_e32 v6, v6, v8
	v_exp_f32_e32 v4, v4
	v_add_f32_e32 v6, v7, v6
	v_exp_f32_e32 v5, v5
	v_add_f32_e32 v2, v2, v6
	v_add_f32_e32 v2, v3, v2
	v_add_f32_e32 v2, v4, v2
	s_add_i32 s31, s31, 1
	v_add_f32_e32 v2, v5, v2
	s_add_i32 s20, s28, s31
	v_add_f32_e32 v54, v54, v2
	v_subrev_u32_e32 v55, 64, v55
	v_lshl_add_u64 v[42:43], v[42:43], 0, s[40:41]
	s_cmp_lg_u32 s20, 2
	v_lshl_add_u64 v[44:45], v[44:45], 0, s[40:41]
	s_barrier
	s_cbranch_scc0 .LBB0_1942
.Lapa1_1934:
	s_add_i32 s20, s31, -2
	s_and_b32 s20, s20, 1
	s_add_i32 s21, s31, -1
	s_cmp_ge_u32 s21, s29
	s_cbranch_scc1 .Lapa1_1936
	s_xor_b32 s21, s20, 1
	s_mulk_i32 s21, 0x4800
	v_or_b32_e32 v2, s21, v111
	v_lshl_add_u32 v3, v154, 1, v2
	v_lshl_add_u32 v2, v152, 1, v2
	s_waitcnt vmcnt(11)
	ds_write_b128 v2, v[82:85]
	s_waitcnt vmcnt(10)
	ds_write_b128 v3, v[86:89]
.Lapa1_1936:
	s_cmp_ge_u32 s31, s29
	s_cbranch_scc1 .Lapa1_1938
.Lapa1_1938:
	s_mulk_i32 s20, 0x4800
	v_add_u32_e32 v50, s20, v156
	ds_read_b128 v[2:5], v50
	ds_read_b128 v[6:9], v50 offset:32
	s_waitcnt lgkmcnt(1)
	v_mfma_f32_32x32x16_bf16 v[18:33], v[2:5], v[78:81], 0
	s_waitcnt lgkmcnt(0)
	v_mfma_f32_32x32x16_bf16 v[18:33], v[6:9], v[66:69], v[18:33]
	ds_read_b128 v[2:5], v50 offset:64
	ds_read_b128 v[6:9], v50 offset:96
	s_waitcnt lgkmcnt(1)
	v_mfma_f32_32x32x16_bf16 v[18:33], v[2:5], v[70:73], v[18:33]
	ds_read_b128 v[2:5], v50 offset:4608
	ds_read_b128 v[46:49], v50 offset:4640
	s_waitcnt lgkmcnt(2)
	v_mfma_f32_32x32x16_bf16 v[18:33], v[6:9], v[74:77], v[18:33]
	s_waitcnt lgkmcnt(1)
	v_mfma_f32_32x32x16_bf16 v[2:17], v[2:5], v[78:81], 0
	s_waitcnt lgkmcnt(0)
	v_mfma_f32_32x32x16_bf16 v[2:17], v[46:49], v[66:69], v[2:17]
	ds_read_b128 v[46:49], v50 offset:4672
	ds_read_b128 v[50:53], v50 offset:4704
	s_waitcnt lgkmcnt(1)
	v_mfma_f32_32x32x16_bf16 v[2:17], v[46:49], v[70:73], v[2:17]
	s_waitcnt lgkmcnt(0)
	v_mfma_f32_32x32x16_bf16 v[2:17], v[50:53], v[74:77], v[2:17]
	v_cmp_lt_i32_e32 vcc, 26, v55
	s_nop 0
	v_fma_f32 v18, v18, s48, v100
	v_fma_f32 v19, v19, s48, v101
	v_fma_f32 v20, v20, s48, v100
	v_fma_f32 v21, v21, s48, v101
	v_pk_fma_f32 v[22:23], v[22:23], s[48:49], v[100:101] op_sel_hi:[1,0,1]
	v_pk_fma_f32 v[24:25], v[24:25], s[48:49], v[100:101] op_sel_hi:[1,0,1]
	v_pk_fma_f32 v[26:27], v[26:27], s[48:49], v[100:101] op_sel_hi:[1,0,1]
	v_pk_fma_f32 v[28:29], v[28:29], s[48:49], v[100:101] op_sel_hi:[1,0,1]
	v_pk_fma_f32 v[30:31], v[30:31], s[48:49], v[100:101] op_sel_hi:[1,0,1]
	s_cmp_eq_u64 vcc, exec
	v_pk_fma_f32 v[32:33], v[32:33], s[48:49], v[100:101] op_sel_hi:[1,0,1]
	s_cbranch_scc1 .Lapa1_1940
	v_cmp_lt_i32_e64 s[20:21], -1, v55
	v_cndmask_b32_e32 v33, v213, v33, vcc
	s_nop 0
	v_cndmask_b32_e64 v18, v213, v18, s[20:21]
	v_cmp_lt_i32_e64 s[20:21], 0, v55
	s_nop 1
	v_cndmask_b32_e64 v19, v213, v19, s[20:21]
	v_cmp_lt_i32_e64 s[20:21], 1, v55
	s_nop 1
	v_cndmask_b32_e64 v20, v213, v20, s[20:21]
	v_cmp_lt_i32_e64 s[20:21], 2, v55
	s_nop 1
	v_cndmask_b32_e64 v21, v213, v21, s[20:21]
	v_cmp_lt_i32_e64 s[20:21], 7, v55
	s_nop 1
	v_cndmask_b32_e64 v22, v213, v22, s[20:21]
	v_cmp_lt_i32_e64 s[20:21], 8, v55
	s_nop 1
	v_cndmask_b32_e64 v23, v213, v23, s[20:21]
	v_cmp_lt_i32_e64 s[20:21], 9, v55
	s_nop 1
	v_cndmask_b32_e64 v24, v213, v24, s[20:21]
	v_cmp_lt_i32_e64 s[20:21], 10, v55
	s_nop 1
	v_cndmask_b32_e64 v25, v213, v25, s[20:21]
	v_cmp_lt_i32_e64 s[20:21], 15, v55
	s_nop 1
	v_cndmask_b32_e64 v26, v213, v26, s[20:21]
	v_cmp_lt_i32_e64 s[20:21], 16, v55
	s_nop 1
	v_cndmask_b32_e64 v27, v213, v27, s[20:21]
	v_cmp_lt_i32_e64 s[20:21], 17, v55
	s_nop 1
	v_cndmask_b32_e64 v28, v213, v28, s[20:21]
	v_cmp_lt_i32_e64 s[20:21], 18, v55
	s_nop 1
	v_cndmask_b32_e64 v29, v213, v29, s[20:21]
	v_cmp_lt_i32_e64 s[20:21], 23, v55
	s_nop 1
	v_cndmask_b32_e64 v30, v213, v30, s[20:21]
	v_cmp_lt_i32_e64 s[20:21], 24, v55
	s_nop 1
	v_cndmask_b32_e64 v31, v213, v31, s[20:21]
	v_cmp_lt_i32_e64 s[20:21], 25, v55
	s_nop 1
	v_cndmask_b32_e64 v32, v213, v32, s[20:21]
.Lapa1_1940:
	v_subrev_u32_e32 v56, 32, v55
	v_cmp_lt_i32_e32 vcc, 26, v56
	v_pk_fma_f32 v[52:53], v[2:3], s[48:49], v[100:101] op_sel_hi:[1,0,1]
	v_pk_fma_f32 v[50:51], v[4:5], s[48:49], v[100:101] op_sel_hi:[1,0,1]
	v_pk_fma_f32 v[48:49], v[6:7], s[48:49], v[100:101] op_sel_hi:[1,0,1]
	v_pk_fma_f32 v[46:47], v[8:9], s[48:49], v[100:101] op_sel_hi:[1,0,1]
	v_pk_fma_f32 v[8:9], v[10:11], s[48:49], v[100:101] op_sel_hi:[1,0,1]
	v_pk_fma_f32 v[6:7], v[12:13], s[48:49], v[100:101] op_sel_hi:[1,0,1]
	v_pk_fma_f32 v[2:3], v[14:15], s[48:49], v[100:101] op_sel_hi:[1,0,1]
	s_cmp_eq_u64 vcc, exec
	v_pk_fma_f32 v[4:5], v[16:17], s[48:49], v[100:101] op_sel_hi:[1,0,1]
	s_cbranch_scc1 .Lapa1_1933
	v_cmp_lt_i32_e64 s[20:21], -1, v56
	v_cndmask_b32_e32 v5, v213, v5, vcc
	s_nop 0
	v_cndmask_b32_e64 v52, v213, v52, s[20:21]
	v_cmp_lt_i32_e64 s[20:21], 0, v56
	s_nop 1
	v_cndmask_b32_e64 v53, v213, v53, s[20:21]
	v_cmp_lt_i32_e64 s[20:21], 1, v56
	s_nop 1
	v_cndmask_b32_e64 v50, v213, v50, s[20:21]
	v_cmp_lt_i32_e64 s[20:21], 2, v56
	s_nop 1
	v_cndmask_b32_e64 v51, v213, v51, s[20:21]
	v_cmp_lt_i32_e64 s[20:21], 7, v56
	s_nop 1
	v_cndmask_b32_e64 v48, v213, v48, s[20:21]
	v_cmp_lt_i32_e64 s[20:21], 8, v56
	s_nop 1
	v_cndmask_b32_e64 v49, v213, v49, s[20:21]
	v_cmp_lt_i32_e64 s[20:21], 9, v56
	s_nop 1
	v_cndmask_b32_e64 v46, v213, v46, s[20:21]
	v_cmp_lt_i32_e64 s[20:21], 10, v56
	s_nop 1
	v_cndmask_b32_e64 v47, v213, v47, s[20:21]
	v_cmp_lt_i32_e64 s[20:21], 15, v56
	s_nop 1
	v_cndmask_b32_e64 v8, v213, v8, s[20:21]
	v_cmp_lt_i32_e64 s[20:21], 16, v56
	s_nop 1
	v_cndmask_b32_e64 v9, v213, v9, s[20:21]
	v_cmp_lt_i32_e64 s[20:21], 17, v56
	s_nop 1
	v_cndmask_b32_e64 v6, v213, v6, s[20:21]
	v_cmp_lt_i32_e64 s[20:21], 18, v56
	s_nop 1
	v_cndmask_b32_e64 v7, v213, v7, s[20:21]
	v_cmp_lt_i32_e64 s[20:21], 23, v56
	s_nop 1
	v_cndmask_b32_e64 v2, v213, v2, s[20:21]
	v_cmp_lt_i32_e64 s[20:21], 24, v56
	s_nop 1
	v_cndmask_b32_e64 v3, v213, v3, s[20:21]
	v_cmp_lt_i32_e64 s[20:21], 25, v56
	s_nop 1
	v_cndmask_b32_e64 v4, v213, v4, s[20:21]
	s_branch .Lapa1_1933
.Lapa1_1933:
	v_exp_f32_e32 v10, v18
	v_exp_f32_e32 v11, v19
	v_exp_f32_e32 v12, v20
	v_exp_f32_e32 v13, v21
	v_exp_f32_e32 v14, v22
	v_add_f32_e32 v10, 0, v10
	v_exp_f32_e32 v15, v23
	v_add_f32_e32 v10, v11, v10
	v_exp_f32_e32 v16, v24
	v_add_f32_e32 v10, v12, v10
	v_exp_f32_e32 v17, v25
	v_add_f32_e32 v10, v13, v10
	v_exp_f32_e32 v18, v26
	v_add_f32_e32 v10, v14, v10
	v_exp_f32_e32 v19, v27
	v_add_f32_e32 v10, v15, v10
	v_exp_f32_e32 v20, v28
	v_add_f32_e32 v10, v16, v10
	v_exp_f32_e32 v21, v29
	v_add_f32_e32 v10, v17, v10
	v_exp_f32_e32 v22, v30
	v_add_f32_e32 v10, v18, v10
	v_exp_f32_e32 v23, v31
	v_add_f32_e32 v10, v19, v10
	v_exp_f32_e32 v24, v32
	v_add_f32_e32 v10, v20, v10
	v_exp_f32_e32 v25, v33
	v_add_f32_e32 v10, v21, v10
	v_add_f32_e32 v10, v22, v10
	v_exp_f32_e32 v11, v52
	v_add_f32_e32 v10, v23, v10
	v_exp_f32_e32 v12, v53
	v_add_f32_e32 v10, v24, v10
	v_exp_f32_e32 v13, v50
	v_add_f32_e32 v10, v25, v10
	v_exp_f32_e32 v14, v51
	v_add_f32_e32 v10, v10, v11
	v_exp_f32_e32 v11, v48
	v_add_f32_e32 v10, v12, v10
	v_exp_f32_e32 v12, v49
	v_add_f32_e32 v10, v13, v10
	v_exp_f32_e32 v13, v46
	v_add_f32_e32 v10, v14, v10
	v_exp_f32_e32 v14, v47
	v_add_f32_e32 v10, v11, v10
	v_exp_f32_e32 v8, v8
	v_add_f32_e32 v10, v12, v10
	v_exp_f32_e32 v9, v9
	v_add_f32_e32 v10, v13, v10
	v_exp_f32_e32 v6, v6
	v_add_f32_e32 v10, v14, v10
	v_exp_f32_e32 v7, v7
	v_add_f32_e32 v8, v8, v10
	v_exp_f32_e32 v2, v2
	v_add_f32_e32 v8, v9, v8
	v_exp_f32_e32 v3, v3
	v_add_f32_e32 v6, v6, v8
	v_exp_f32_e32 v4, v4
	v_add_f32_e32 v6, v7, v6
	v_exp_f32_e32 v5, v5
	v_add_f32_e32 v2, v2, v6
	v_add_f32_e32 v2, v3, v2
	v_add_f32_e32 v2, v4, v2
	s_add_i32 s31, s31, 1
	v_add_f32_e32 v2, v5, v2
	s_add_i32 s20, s28, s31
	v_add_f32_e32 v54, v54, v2
	v_subrev_u32_e32 v55, 64, v55
	v_lshl_add_u64 v[42:43], v[42:43], 0, s[40:41]
	s_cmp_lg_u32 s20, 2
	v_lshl_add_u64 v[44:45], v[44:45], 0, s[40:41]
	s_barrier
	s_cbranch_scc0 .LBB0_1942
.Lapa2_1934:
	s_add_i32 s20, s31, -2
	s_and_b32 s20, s20, 1
	s_add_i32 s21, s31, -1
	s_cmp_ge_u32 s21, s29
	s_cbranch_scc1 .Lapa2_1936
	s_xor_b32 s21, s20, 1
	s_mulk_i32 s21, 0x4800
	v_or_b32_e32 v2, s21, v111
	v_lshl_add_u32 v3, v154, 1, v2
	v_lshl_add_u32 v2, v152, 1, v2
	s_waitcnt vmcnt(9)
	ds_write_b128 v2, v[90:93]
	s_waitcnt vmcnt(8)
	ds_write_b128 v3, v[94:97]
.Lapa2_1936:
	s_cmp_ge_u32 s31, s29
	s_cbranch_scc1 .Lapa2_1938
.Lapa2_1938:
	s_mulk_i32 s20, 0x4800
	v_add_u32_e32 v50, s20, v156
	ds_read_b128 v[2:5], v50
	ds_read_b128 v[6:9], v50 offset:32
	s_waitcnt lgkmcnt(1)
	v_mfma_f32_32x32x16_bf16 v[18:33], v[2:5], v[78:81], 0
	s_waitcnt lgkmcnt(0)
	v_mfma_f32_32x32x16_bf16 v[18:33], v[6:9], v[66:69], v[18:33]
	ds_read_b128 v[2:5], v50 offset:64
	ds_read_b128 v[6:9], v50 offset:96
	s_waitcnt lgkmcnt(1)
	v_mfma_f32_32x32x16_bf16 v[18:33], v[2:5], v[70:73], v[18:33]
	ds_read_b128 v[2:5], v50 offset:4608
	ds_read_b128 v[46:49], v50 offset:4640
	s_waitcnt lgkmcnt(2)
	v_mfma_f32_32x32x16_bf16 v[18:33], v[6:9], v[74:77], v[18:33]
	s_waitcnt lgkmcnt(1)
	v_mfma_f32_32x32x16_bf16 v[2:17], v[2:5], v[78:81], 0
	s_waitcnt lgkmcnt(0)
	v_mfma_f32_32x32x16_bf16 v[2:17], v[46:49], v[66:69], v[2:17]
	ds_read_b128 v[46:49], v50 offset:4672
	ds_read_b128 v[50:53], v50 offset:4704
	s_waitcnt lgkmcnt(1)
	v_mfma_f32_32x32x16_bf16 v[2:17], v[46:49], v[70:73], v[2:17]
	s_waitcnt lgkmcnt(0)
	v_mfma_f32_32x32x16_bf16 v[2:17], v[50:53], v[74:77], v[2:17]
	v_cmp_lt_i32_e32 vcc, 26, v55
	s_nop 0
	v_fma_f32 v18, v18, s48, v100
	v_fma_f32 v19, v19, s48, v101
	v_fma_f32 v20, v20, s48, v100
	v_fma_f32 v21, v21, s48, v101
	v_pk_fma_f32 v[22:23], v[22:23], s[48:49], v[100:101] op_sel_hi:[1,0,1]
	v_pk_fma_f32 v[24:25], v[24:25], s[48:49], v[100:101] op_sel_hi:[1,0,1]
	v_pk_fma_f32 v[26:27], v[26:27], s[48:49], v[100:101] op_sel_hi:[1,0,1]
	v_pk_fma_f32 v[28:29], v[28:29], s[48:49], v[100:101] op_sel_hi:[1,0,1]
	v_pk_fma_f32 v[30:31], v[30:31], s[48:49], v[100:101] op_sel_hi:[1,0,1]
	s_cmp_eq_u64 vcc, exec
	v_pk_fma_f32 v[32:33], v[32:33], s[48:49], v[100:101] op_sel_hi:[1,0,1]
	s_cbranch_scc1 .Lapa2_1940
	v_cmp_lt_i32_e64 s[20:21], -1, v55
	v_cndmask_b32_e32 v33, v213, v33, vcc
	s_nop 0
	v_cndmask_b32_e64 v18, v213, v18, s[20:21]
	v_cmp_lt_i32_e64 s[20:21], 0, v55
	s_nop 1
	v_cndmask_b32_e64 v19, v213, v19, s[20:21]
	v_cmp_lt_i32_e64 s[20:21], 1, v55
	s_nop 1
	v_cndmask_b32_e64 v20, v213, v20, s[20:21]
	v_cmp_lt_i32_e64 s[20:21], 2, v55
	s_nop 1
	v_cndmask_b32_e64 v21, v213, v21, s[20:21]
	v_cmp_lt_i32_e64 s[20:21], 7, v55
	s_nop 1
	v_cndmask_b32_e64 v22, v213, v22, s[20:21]
	v_cmp_lt_i32_e64 s[20:21], 8, v55
	s_nop 1
	v_cndmask_b32_e64 v23, v213, v23, s[20:21]
	v_cmp_lt_i32_e64 s[20:21], 9, v55
	s_nop 1
	v_cndmask_b32_e64 v24, v213, v24, s[20:21]
	v_cmp_lt_i32_e64 s[20:21], 10, v55
	s_nop 1
	v_cndmask_b32_e64 v25, v213, v25, s[20:21]
	v_cmp_lt_i32_e64 s[20:21], 15, v55
	s_nop 1
	v_cndmask_b32_e64 v26, v213, v26, s[20:21]
	v_cmp_lt_i32_e64 s[20:21], 16, v55
	s_nop 1
	v_cndmask_b32_e64 v27, v213, v27, s[20:21]
	v_cmp_lt_i32_e64 s[20:21], 17, v55
	s_nop 1
	v_cndmask_b32_e64 v28, v213, v28, s[20:21]
	v_cmp_lt_i32_e64 s[20:21], 18, v55
	s_nop 1
	v_cndmask_b32_e64 v29, v213, v29, s[20:21]
	v_cmp_lt_i32_e64 s[20:21], 23, v55
	s_nop 1
	v_cndmask_b32_e64 v30, v213, v30, s[20:21]
	v_cmp_lt_i32_e64 s[20:21], 24, v55
	s_nop 1
	v_cndmask_b32_e64 v31, v213, v31, s[20:21]
	v_cmp_lt_i32_e64 s[20:21], 25, v55
	s_nop 1
	v_cndmask_b32_e64 v32, v213, v32, s[20:21]
.Lapa2_1940:
	v_subrev_u32_e32 v56, 32, v55
	v_cmp_lt_i32_e32 vcc, 26, v56
	v_pk_fma_f32 v[52:53], v[2:3], s[48:49], v[100:101] op_sel_hi:[1,0,1]
	v_pk_fma_f32 v[50:51], v[4:5], s[48:49], v[100:101] op_sel_hi:[1,0,1]
	v_pk_fma_f32 v[48:49], v[6:7], s[48:49], v[100:101] op_sel_hi:[1,0,1]
	v_pk_fma_f32 v[46:47], v[8:9], s[48:49], v[100:101] op_sel_hi:[1,0,1]
	v_pk_fma_f32 v[8:9], v[10:11], s[48:49], v[100:101] op_sel_hi:[1,0,1]
	v_pk_fma_f32 v[6:7], v[12:13], s[48:49], v[100:101] op_sel_hi:[1,0,1]
	v_pk_fma_f32 v[2:3], v[14:15], s[48:49], v[100:101] op_sel_hi:[1,0,1]
	s_cmp_eq_u64 vcc, exec
	v_pk_fma_f32 v[4:5], v[16:17], s[48:49], v[100:101] op_sel_hi:[1,0,1]
	s_cbranch_scc1 .Lapa2_1933
	v_cmp_lt_i32_e64 s[20:21], -1, v56
	v_cndmask_b32_e32 v5, v213, v5, vcc
	s_nop 0
	v_cndmask_b32_e64 v52, v213, v52, s[20:21]
	v_cmp_lt_i32_e64 s[20:21], 0, v56
	s_nop 1
	v_cndmask_b32_e64 v53, v213, v53, s[20:21]
	v_cmp_lt_i32_e64 s[20:21], 1, v56
	s_nop 1
	v_cndmask_b32_e64 v50, v213, v50, s[20:21]
	v_cmp_lt_i32_e64 s[20:21], 2, v56
	s_nop 1
	v_cndmask_b32_e64 v51, v213, v51, s[20:21]
	v_cmp_lt_i32_e64 s[20:21], 7, v56
	s_nop 1
	v_cndmask_b32_e64 v48, v213, v48, s[20:21]
	v_cmp_lt_i32_e64 s[20:21], 8, v56
	s_nop 1
	v_cndmask_b32_e64 v49, v213, v49, s[20:21]
	v_cmp_lt_i32_e64 s[20:21], 9, v56
	s_nop 1
	v_cndmask_b32_e64 v46, v213, v46, s[20:21]
	v_cmp_lt_i32_e64 s[20:21], 10, v56
	s_nop 1
	v_cndmask_b32_e64 v47, v213, v47, s[20:21]
	v_cmp_lt_i32_e64 s[20:21], 15, v56
	s_nop 1
	v_cndmask_b32_e64 v8, v213, v8, s[20:21]
	v_cmp_lt_i32_e64 s[20:21], 16, v56
	s_nop 1
	v_cndmask_b32_e64 v9, v213, v9, s[20:21]
	v_cmp_lt_i32_e64 s[20:21], 17, v56
	s_nop 1
	v_cndmask_b32_e64 v6, v213, v6, s[20:21]
	v_cmp_lt_i32_e64 s[20:21], 18, v56
	s_nop 1
	v_cndmask_b32_e64 v7, v213, v7, s[20:21]
	v_cmp_lt_i32_e64 s[20:21], 23, v56
	s_nop 1
	v_cndmask_b32_e64 v2, v213, v2, s[20:21]
	v_cmp_lt_i32_e64 s[20:21], 24, v56
	s_nop 1
	v_cndmask_b32_e64 v3, v213, v3, s[20:21]
	v_cmp_lt_i32_e64 s[20:21], 25, v56
	s_nop 1
	v_cndmask_b32_e64 v4, v213, v4, s[20:21]
	s_branch .Lapa2_1933
.Lapa2_1933:
	v_exp_f32_e32 v10, v18
	v_exp_f32_e32 v11, v19
	v_exp_f32_e32 v12, v20
	v_exp_f32_e32 v13, v21
	v_exp_f32_e32 v14, v22
	v_add_f32_e32 v10, 0, v10
	v_exp_f32_e32 v15, v23
	v_add_f32_e32 v10, v11, v10
	v_exp_f32_e32 v16, v24
	v_add_f32_e32 v10, v12, v10
	v_exp_f32_e32 v17, v25
	v_add_f32_e32 v10, v13, v10
	v_exp_f32_e32 v18, v26
	v_add_f32_e32 v10, v14, v10
	v_exp_f32_e32 v19, v27
	v_add_f32_e32 v10, v15, v10
	v_exp_f32_e32 v20, v28
	v_add_f32_e32 v10, v16, v10
	v_exp_f32_e32 v21, v29
	v_add_f32_e32 v10, v17, v10
	v_exp_f32_e32 v22, v30
	v_add_f32_e32 v10, v18, v10
	v_exp_f32_e32 v23, v31
	v_add_f32_e32 v10, v19, v10
	v_exp_f32_e32 v24, v32
	v_add_f32_e32 v10, v20, v10
	v_exp_f32_e32 v25, v33
	v_add_f32_e32 v10, v21, v10
	v_add_f32_e32 v10, v22, v10
	v_exp_f32_e32 v11, v52
	v_add_f32_e32 v10, v23, v10
	v_exp_f32_e32 v12, v53
	v_add_f32_e32 v10, v24, v10
	v_exp_f32_e32 v13, v50
	v_add_f32_e32 v10, v25, v10
	v_exp_f32_e32 v14, v51
	v_add_f32_e32 v10, v10, v11
	v_exp_f32_e32 v11, v48
	v_add_f32_e32 v10, v12, v10
	v_exp_f32_e32 v12, v49
	v_add_f32_e32 v10, v13, v10
	v_exp_f32_e32 v13, v46
	v_add_f32_e32 v10, v14, v10
	v_exp_f32_e32 v14, v47
	v_add_f32_e32 v10, v11, v10
	v_exp_f32_e32 v8, v8
	v_add_f32_e32 v10, v12, v10
	v_exp_f32_e32 v9, v9
	v_add_f32_e32 v10, v13, v10
	v_exp_f32_e32 v6, v6
	v_add_f32_e32 v10, v14, v10
	v_exp_f32_e32 v7, v7
	v_add_f32_e32 v8, v8, v10
	v_exp_f32_e32 v2, v2
	v_add_f32_e32 v8, v9, v8
	v_exp_f32_e32 v3, v3
	v_add_f32_e32 v6, v6, v8
	v_exp_f32_e32 v4, v4
	v_add_f32_e32 v6, v7, v6
	v_exp_f32_e32 v5, v5
	v_add_f32_e32 v2, v2, v6
	v_add_f32_e32 v2, v3, v2
	v_add_f32_e32 v2, v4, v2
	s_add_i32 s31, s31, 1
	v_add_f32_e32 v2, v5, v2
	s_add_i32 s20, s28, s31
	v_add_f32_e32 v54, v54, v2
	v_subrev_u32_e32 v55, 64, v55
	v_lshl_add_u64 v[42:43], v[42:43], 0, s[40:41]
	s_cmp_lg_u32 s20, 2
	v_lshl_add_u64 v[44:45], v[44:45], 0, s[40:41]
	s_barrier
	s_cbranch_scc0 .LBB0_1942
.Lapa3_1934:
	s_add_i32 s20, s31, -2
	s_and_b32 s20, s20, 1
	s_add_i32 s21, s31, -1
	s_cmp_ge_u32 s21, s29
	s_cbranch_scc1 .Lapa3_1936
	s_xor_b32 s21, s20, 1
	s_mulk_i32 s21, 0x4800
	v_or_b32_e32 v2, s21, v111
	v_lshl_add_u32 v3, v154, 1, v2
	v_lshl_add_u32 v2, v152, 1, v2
	s_waitcnt vmcnt(7)
	ds_write_b128 v2, v[134:137]
	s_waitcnt vmcnt(6)
	ds_write_b128 v3, v[138:141]
.Lapa3_1936:
	s_cmp_ge_u32 s31, s29
	s_cbranch_scc1 .Lapa3_1938
.Lapa3_1938:
	s_mulk_i32 s20, 0x4800
	v_add_u32_e32 v50, s20, v156
	ds_read_b128 v[2:5], v50
	ds_read_b128 v[6:9], v50 offset:32
	s_waitcnt lgkmcnt(1)
	v_mfma_f32_32x32x16_bf16 v[18:33], v[2:5], v[78:81], 0
	s_waitcnt lgkmcnt(0)
	v_mfma_f32_32x32x16_bf16 v[18:33], v[6:9], v[66:69], v[18:33]
	ds_read_b128 v[2:5], v50 offset:64
	ds_read_b128 v[6:9], v50 offset:96
	s_waitcnt lgkmcnt(1)
	v_mfma_f32_32x32x16_bf16 v[18:33], v[2:5], v[70:73], v[18:33]
	ds_read_b128 v[2:5], v50 offset:4608
	ds_read_b128 v[46:49], v50 offset:4640
	s_waitcnt lgkmcnt(2)
	v_mfma_f32_32x32x16_bf16 v[18:33], v[6:9], v[74:77], v[18:33]
	s_waitcnt lgkmcnt(1)
	v_mfma_f32_32x32x16_bf16 v[2:17], v[2:5], v[78:81], 0
	s_waitcnt lgkmcnt(0)
	v_mfma_f32_32x32x16_bf16 v[2:17], v[46:49], v[66:69], v[2:17]
	ds_read_b128 v[46:49], v50 offset:4672
	ds_read_b128 v[50:53], v50 offset:4704
	s_waitcnt lgkmcnt(1)
	v_mfma_f32_32x32x16_bf16 v[2:17], v[46:49], v[70:73], v[2:17]
	s_waitcnt lgkmcnt(0)
	v_mfma_f32_32x32x16_bf16 v[2:17], v[50:53], v[74:77], v[2:17]
	v_cmp_lt_i32_e32 vcc, 26, v55
	s_nop 0
	v_fma_f32 v18, v18, s48, v100
	v_fma_f32 v19, v19, s48, v101
	v_fma_f32 v20, v20, s48, v100
	v_fma_f32 v21, v21, s48, v101
	v_pk_fma_f32 v[22:23], v[22:23], s[48:49], v[100:101] op_sel_hi:[1,0,1]
	v_pk_fma_f32 v[24:25], v[24:25], s[48:49], v[100:101] op_sel_hi:[1,0,1]
	v_pk_fma_f32 v[26:27], v[26:27], s[48:49], v[100:101] op_sel_hi:[1,0,1]
	v_pk_fma_f32 v[28:29], v[28:29], s[48:49], v[100:101] op_sel_hi:[1,0,1]
	v_pk_fma_f32 v[30:31], v[30:31], s[48:49], v[100:101] op_sel_hi:[1,0,1]
	s_cmp_eq_u64 vcc, exec
	v_pk_fma_f32 v[32:33], v[32:33], s[48:49], v[100:101] op_sel_hi:[1,0,1]
	s_cbranch_scc1 .Lapa3_1940
	v_cmp_lt_i32_e64 s[20:21], -1, v55
	v_cndmask_b32_e32 v33, v213, v33, vcc
	s_nop 0
	v_cndmask_b32_e64 v18, v213, v18, s[20:21]
	v_cmp_lt_i32_e64 s[20:21], 0, v55
	s_nop 1
	v_cndmask_b32_e64 v19, v213, v19, s[20:21]
	v_cmp_lt_i32_e64 s[20:21], 1, v55
	s_nop 1
	v_cndmask_b32_e64 v20, v213, v20, s[20:21]
	v_cmp_lt_i32_e64 s[20:21], 2, v55
	s_nop 1
	v_cndmask_b32_e64 v21, v213, v21, s[20:21]
	v_cmp_lt_i32_e64 s[20:21], 7, v55
	s_nop 1
	v_cndmask_b32_e64 v22, v213, v22, s[20:21]
	v_cmp_lt_i32_e64 s[20:21], 8, v55
	s_nop 1
	v_cndmask_b32_e64 v23, v213, v23, s[20:21]
	v_cmp_lt_i32_e64 s[20:21], 9, v55
	s_nop 1
	v_cndmask_b32_e64 v24, v213, v24, s[20:21]
	v_cmp_lt_i32_e64 s[20:21], 10, v55
	s_nop 1
	v_cndmask_b32_e64 v25, v213, v25, s[20:21]
	v_cmp_lt_i32_e64 s[20:21], 15, v55
	s_nop 1
	v_cndmask_b32_e64 v26, v213, v26, s[20:21]
	v_cmp_lt_i32_e64 s[20:21], 16, v55
	s_nop 1
	v_cndmask_b32_e64 v27, v213, v27, s[20:21]
	v_cmp_lt_i32_e64 s[20:21], 17, v55
	s_nop 1
	v_cndmask_b32_e64 v28, v213, v28, s[20:21]
	v_cmp_lt_i32_e64 s[20:21], 18, v55
	s_nop 1
	v_cndmask_b32_e64 v29, v213, v29, s[20:21]
	v_cmp_lt_i32_e64 s[20:21], 23, v55
	s_nop 1
	v_cndmask_b32_e64 v30, v213, v30, s[20:21]
	v_cmp_lt_i32_e64 s[20:21], 24, v55
	s_nop 1
	v_cndmask_b32_e64 v31, v213, v31, s[20:21]
	v_cmp_lt_i32_e64 s[20:21], 25, v55
	s_nop 1
	v_cndmask_b32_e64 v32, v213, v32, s[20:21]
.Lapa3_1940:
	v_subrev_u32_e32 v56, 32, v55
	v_cmp_lt_i32_e32 vcc, 26, v56
	v_pk_fma_f32 v[52:53], v[2:3], s[48:49], v[100:101] op_sel_hi:[1,0,1]
	v_pk_fma_f32 v[50:51], v[4:5], s[48:49], v[100:101] op_sel_hi:[1,0,1]
	v_pk_fma_f32 v[48:49], v[6:7], s[48:49], v[100:101] op_sel_hi:[1,0,1]
	v_pk_fma_f32 v[46:47], v[8:9], s[48:49], v[100:101] op_sel_hi:[1,0,1]
	v_pk_fma_f32 v[8:9], v[10:11], s[48:49], v[100:101] op_sel_hi:[1,0,1]
	v_pk_fma_f32 v[6:7], v[12:13], s[48:49], v[100:101] op_sel_hi:[1,0,1]
	v_pk_fma_f32 v[2:3], v[14:15], s[48:49], v[100:101] op_sel_hi:[1,0,1]
	s_cmp_eq_u64 vcc, exec
	v_pk_fma_f32 v[4:5], v[16:17], s[48:49], v[100:101] op_sel_hi:[1,0,1]
	s_cbranch_scc1 .Lapa3_1933
	v_cmp_lt_i32_e64 s[20:21], -1, v56
	v_cndmask_b32_e32 v5, v213, v5, vcc
	s_nop 0
	v_cndmask_b32_e64 v52, v213, v52, s[20:21]
	v_cmp_lt_i32_e64 s[20:21], 0, v56
	s_nop 1
	v_cndmask_b32_e64 v53, v213, v53, s[20:21]
	v_cmp_lt_i32_e64 s[20:21], 1, v56
	s_nop 1
	v_cndmask_b32_e64 v50, v213, v50, s[20:21]
	v_cmp_lt_i32_e64 s[20:21], 2, v56
	s_nop 1
	v_cndmask_b32_e64 v51, v213, v51, s[20:21]
	v_cmp_lt_i32_e64 s[20:21], 7, v56
	s_nop 1
	v_cndmask_b32_e64 v48, v213, v48, s[20:21]
	v_cmp_lt_i32_e64 s[20:21], 8, v56
	s_nop 1
	v_cndmask_b32_e64 v49, v213, v49, s[20:21]
	v_cmp_lt_i32_e64 s[20:21], 9, v56
	s_nop 1
	v_cndmask_b32_e64 v46, v213, v46, s[20:21]
	v_cmp_lt_i32_e64 s[20:21], 10, v56
	s_nop 1
	v_cndmask_b32_e64 v47, v213, v47, s[20:21]
	v_cmp_lt_i32_e64 s[20:21], 15, v56
	s_nop 1
	v_cndmask_b32_e64 v8, v213, v8, s[20:21]
	v_cmp_lt_i32_e64 s[20:21], 16, v56
	s_nop 1
	v_cndmask_b32_e64 v9, v213, v9, s[20:21]
	v_cmp_lt_i32_e64 s[20:21], 17, v56
	s_nop 1
	v_cndmask_b32_e64 v6, v213, v6, s[20:21]
	v_cmp_lt_i32_e64 s[20:21], 18, v56
	s_nop 1
	v_cndmask_b32_e64 v7, v213, v7, s[20:21]
	v_cmp_lt_i32_e64 s[20:21], 23, v56
	s_nop 1
	v_cndmask_b32_e64 v2, v213, v2, s[20:21]
	v_cmp_lt_i32_e64 s[20:21], 24, v56
	s_nop 1
	v_cndmask_b32_e64 v3, v213, v3, s[20:21]
	v_cmp_lt_i32_e64 s[20:21], 25, v56
	s_nop 1
	v_cndmask_b32_e64 v4, v213, v4, s[20:21]
	s_branch .Lapa3_1933
.Lapa3_1933:
	v_exp_f32_e32 v10, v18
	v_exp_f32_e32 v11, v19
	v_exp_f32_e32 v12, v20
	v_exp_f32_e32 v13, v21
	v_exp_f32_e32 v14, v22
	v_add_f32_e32 v10, 0, v10
	v_exp_f32_e32 v15, v23
	v_add_f32_e32 v10, v11, v10
	v_exp_f32_e32 v16, v24
	v_add_f32_e32 v10, v12, v10
	v_exp_f32_e32 v17, v25
	v_add_f32_e32 v10, v13, v10
	v_exp_f32_e32 v18, v26
	v_add_f32_e32 v10, v14, v10
	v_exp_f32_e32 v19, v27
	v_add_f32_e32 v10, v15, v10
	v_exp_f32_e32 v20, v28
	v_add_f32_e32 v10, v16, v10
	v_exp_f32_e32 v21, v29
	v_add_f32_e32 v10, v17, v10
	v_exp_f32_e32 v22, v30
	v_add_f32_e32 v10, v18, v10
	v_exp_f32_e32 v23, v31
	v_add_f32_e32 v10, v19, v10
	v_exp_f32_e32 v24, v32
	v_add_f32_e32 v10, v20, v10
	v_exp_f32_e32 v25, v33
	v_add_f32_e32 v10, v21, v10
	v_add_f32_e32 v10, v22, v10
	v_exp_f32_e32 v11, v52
	v_add_f32_e32 v10, v23, v10
	v_exp_f32_e32 v12, v53
	v_add_f32_e32 v10, v24, v10
	v_exp_f32_e32 v13, v50
	v_add_f32_e32 v10, v25, v10
	v_exp_f32_e32 v14, v51
	v_add_f32_e32 v10, v10, v11
	v_exp_f32_e32 v11, v48
	v_add_f32_e32 v10, v12, v10
	v_exp_f32_e32 v12, v49
	v_add_f32_e32 v10, v13, v10
	v_exp_f32_e32 v13, v46
	v_add_f32_e32 v10, v14, v10
	v_exp_f32_e32 v14, v47
	v_add_f32_e32 v10, v11, v10
	v_exp_f32_e32 v8, v8
	v_add_f32_e32 v10, v12, v10
	v_exp_f32_e32 v9, v9
	v_add_f32_e32 v10, v13, v10
	v_exp_f32_e32 v6, v6
	v_add_f32_e32 v10, v14, v10
	v_exp_f32_e32 v7, v7
	v_add_f32_e32 v8, v8, v10
	v_exp_f32_e32 v2, v2
	v_add_f32_e32 v8, v9, v8
	v_exp_f32_e32 v3, v3
	v_add_f32_e32 v6, v6, v8
	v_exp_f32_e32 v4, v4
	v_add_f32_e32 v6, v7, v6
	v_exp_f32_e32 v5, v5
	v_add_f32_e32 v2, v2, v6
	v_add_f32_e32 v2, v3, v2
	v_add_f32_e32 v2, v4, v2
	s_add_i32 s31, s31, 1
	v_add_f32_e32 v2, v5, v2
	s_add_i32 s20, s28, s31
	v_add_f32_e32 v54, v54, v2
	v_subrev_u32_e32 v55, 64, v55
	v_lshl_add_u64 v[42:43], v[42:43], 0, s[40:41]
	s_cmp_lg_u32 s20, 2
	v_lshl_add_u64 v[44:45], v[44:45], 0, s[40:41]
	s_barrier
	s_cbranch_scc0 .LBB0_1942
.Lapa4_1934:
	s_add_i32 s20, s31, -2
	s_and_b32 s20, s20, 1
	s_add_i32 s21, s31, -1
	s_cmp_ge_u32 s21, s29
	s_cbranch_scc1 .Lapa4_1936
	s_xor_b32 s21, s20, 1
	s_mulk_i32 s21, 0x4800
	v_or_b32_e32 v2, s21, v111
	v_lshl_add_u32 v3, v154, 1, v2
	v_lshl_add_u32 v2, v152, 1, v2
	s_waitcnt vmcnt(5)
	ds_write_b128 v2, v[142:145]
	s_waitcnt vmcnt(4)
	ds_write_b128 v3, v[146:149]
.Lapa4_1936:
	s_cmp_ge_u32 s31, s29
	s_cbranch_scc1 .Lapa4_1938
.Lapa4_1938:
	s_mulk_i32 s20, 0x4800
	v_add_u32_e32 v50, s20, v156
	ds_read_b128 v[2:5], v50
	ds_read_b128 v[6:9], v50 offset:32
	s_waitcnt lgkmcnt(1)
	v_mfma_f32_32x32x16_bf16 v[18:33], v[2:5], v[78:81], 0
	s_waitcnt lgkmcnt(0)
	v_mfma_f32_32x32x16_bf16 v[18:33], v[6:9], v[66:69], v[18:33]
	ds_read_b128 v[2:5], v50 offset:64
	ds_read_b128 v[6:9], v50 offset:96
	s_waitcnt lgkmcnt(1)
	v_mfma_f32_32x32x16_bf16 v[18:33], v[2:5], v[70:73], v[18:33]
	ds_read_b128 v[2:5], v50 offset:4608
	ds_read_b128 v[46:49], v50 offset:4640
	s_waitcnt lgkmcnt(2)
	v_mfma_f32_32x32x16_bf16 v[18:33], v[6:9], v[74:77], v[18:33]
	s_waitcnt lgkmcnt(1)
	v_mfma_f32_32x32x16_bf16 v[2:17], v[2:5], v[78:81], 0
	s_waitcnt lgkmcnt(0)
	v_mfma_f32_32x32x16_bf16 v[2:17], v[46:49], v[66:69], v[2:17]
	ds_read_b128 v[46:49], v50 offset:4672
	ds_read_b128 v[50:53], v50 offset:4704
	s_waitcnt lgkmcnt(1)
	v_mfma_f32_32x32x16_bf16 v[2:17], v[46:49], v[70:73], v[2:17]
	s_waitcnt lgkmcnt(0)
	v_mfma_f32_32x32x16_bf16 v[2:17], v[50:53], v[74:77], v[2:17]
	v_cmp_lt_i32_e32 vcc, 26, v55
	s_nop 0
	v_fma_f32 v18, v18, s48, v100
	v_fma_f32 v19, v19, s48, v101
	v_fma_f32 v20, v20, s48, v100
	v_fma_f32 v21, v21, s48, v101
	v_pk_fma_f32 v[22:23], v[22:23], s[48:49], v[100:101] op_sel_hi:[1,0,1]
	v_pk_fma_f32 v[24:25], v[24:25], s[48:49], v[100:101] op_sel_hi:[1,0,1]
	v_pk_fma_f32 v[26:27], v[26:27], s[48:49], v[100:101] op_sel_hi:[1,0,1]
	v_pk_fma_f32 v[28:29], v[28:29], s[48:49], v[100:101] op_sel_hi:[1,0,1]
	v_pk_fma_f32 v[30:31], v[30:31], s[48:49], v[100:101] op_sel_hi:[1,0,1]
	s_cmp_eq_u64 vcc, exec
	v_pk_fma_f32 v[32:33], v[32:33], s[48:49], v[100:101] op_sel_hi:[1,0,1]
	s_cbranch_scc1 .Lapa4_1940
	v_cmp_lt_i32_e64 s[20:21], -1, v55
	v_cndmask_b32_e32 v33, v213, v33, vcc
	s_nop 0
	v_cndmask_b32_e64 v18, v213, v18, s[20:21]
	v_cmp_lt_i32_e64 s[20:21], 0, v55
	s_nop 1
	v_cndmask_b32_e64 v19, v213, v19, s[20:21]
	v_cmp_lt_i32_e64 s[20:21], 1, v55
	s_nop 1
	v_cndmask_b32_e64 v20, v213, v20, s[20:21]
	v_cmp_lt_i32_e64 s[20:21], 2, v55
	s_nop 1
	v_cndmask_b32_e64 v21, v213, v21, s[20:21]
	v_cmp_lt_i32_e64 s[20:21], 7, v55
	s_nop 1
	v_cndmask_b32_e64 v22, v213, v22, s[20:21]
	v_cmp_lt_i32_e64 s[20:21], 8, v55
	s_nop 1
	v_cndmask_b32_e64 v23, v213, v23, s[20:21]
	v_cmp_lt_i32_e64 s[20:21], 9, v55
	s_nop 1
	v_cndmask_b32_e64 v24, v213, v24, s[20:21]
	v_cmp_lt_i32_e64 s[20:21], 10, v55
	s_nop 1
	v_cndmask_b32_e64 v25, v213, v25, s[20:21]
	v_cmp_lt_i32_e64 s[20:21], 15, v55
	s_nop 1
	v_cndmask_b32_e64 v26, v213, v26, s[20:21]
	v_cmp_lt_i32_e64 s[20:21], 16, v55
	s_nop 1
	v_cndmask_b32_e64 v27, v213, v27, s[20:21]
	v_cmp_lt_i32_e64 s[20:21], 17, v55
	s_nop 1
	v_cndmask_b32_e64 v28, v213, v28, s[20:21]
	v_cmp_lt_i32_e64 s[20:21], 18, v55
	s_nop 1
	v_cndmask_b32_e64 v29, v213, v29, s[20:21]
	v_cmp_lt_i32_e64 s[20:21], 23, v55
	s_nop 1
	v_cndmask_b32_e64 v30, v213, v30, s[20:21]
	v_cmp_lt_i32_e64 s[20:21], 24, v55
	s_nop 1
	v_cndmask_b32_e64 v31, v213, v31, s[20:21]
	v_cmp_lt_i32_e64 s[20:21], 25, v55
	s_nop 1
	v_cndmask_b32_e64 v32, v213, v32, s[20:21]
.Lapa4_1940:
	v_subrev_u32_e32 v56, 32, v55
	v_cmp_lt_i32_e32 vcc, 26, v56
	v_pk_fma_f32 v[52:53], v[2:3], s[48:49], v[100:101] op_sel_hi:[1,0,1]
	v_pk_fma_f32 v[50:51], v[4:5], s[48:49], v[100:101] op_sel_hi:[1,0,1]
	v_pk_fma_f32 v[48:49], v[6:7], s[48:49], v[100:101] op_sel_hi:[1,0,1]
	v_pk_fma_f32 v[46:47], v[8:9], s[48:49], v[100:101] op_sel_hi:[1,0,1]
	v_pk_fma_f32 v[8:9], v[10:11], s[48:49], v[100:101] op_sel_hi:[1,0,1]
	v_pk_fma_f32 v[6:7], v[12:13], s[48:49], v[100:101] op_sel_hi:[1,0,1]
	v_pk_fma_f32 v[2:3], v[14:15], s[48:49], v[100:101] op_sel_hi:[1,0,1]
	s_cmp_eq_u64 vcc, exec
	v_pk_fma_f32 v[4:5], v[16:17], s[48:49], v[100:101] op_sel_hi:[1,0,1]
	s_cbranch_scc1 .Lapa4_1933
	v_cmp_lt_i32_e64 s[20:21], -1, v56
	v_cndmask_b32_e32 v5, v213, v5, vcc
	s_nop 0
	v_cndmask_b32_e64 v52, v213, v52, s[20:21]
	v_cmp_lt_i32_e64 s[20:21], 0, v56
	s_nop 1
	v_cndmask_b32_e64 v53, v213, v53, s[20:21]
	v_cmp_lt_i32_e64 s[20:21], 1, v56
	s_nop 1
	v_cndmask_b32_e64 v50, v213, v50, s[20:21]
	v_cmp_lt_i32_e64 s[20:21], 2, v56
	s_nop 1
	v_cndmask_b32_e64 v51, v213, v51, s[20:21]
	v_cmp_lt_i32_e64 s[20:21], 7, v56
	s_nop 1
	v_cndmask_b32_e64 v48, v213, v48, s[20:21]
	v_cmp_lt_i32_e64 s[20:21], 8, v56
	s_nop 1
	v_cndmask_b32_e64 v49, v213, v49, s[20:21]
	v_cmp_lt_i32_e64 s[20:21], 9, v56
	s_nop 1
	v_cndmask_b32_e64 v46, v213, v46, s[20:21]
	v_cmp_lt_i32_e64 s[20:21], 10, v56
	s_nop 1
	v_cndmask_b32_e64 v47, v213, v47, s[20:21]
	v_cmp_lt_i32_e64 s[20:21], 15, v56
	s_nop 1
	v_cndmask_b32_e64 v8, v213, v8, s[20:21]
	v_cmp_lt_i32_e64 s[20:21], 16, v56
	s_nop 1
	v_cndmask_b32_e64 v9, v213, v9, s[20:21]
	v_cmp_lt_i32_e64 s[20:21], 17, v56
	s_nop 1
	v_cndmask_b32_e64 v6, v213, v6, s[20:21]
	v_cmp_lt_i32_e64 s[20:21], 18, v56
	s_nop 1
	v_cndmask_b32_e64 v7, v213, v7, s[20:21]
	v_cmp_lt_i32_e64 s[20:21], 23, v56
	s_nop 1
	v_cndmask_b32_e64 v2, v213, v2, s[20:21]
	v_cmp_lt_i32_e64 s[20:21], 24, v56
	s_nop 1
	v_cndmask_b32_e64 v3, v213, v3, s[20:21]
	v_cmp_lt_i32_e64 s[20:21], 25, v56
	s_nop 1
	v_cndmask_b32_e64 v4, v213, v4, s[20:21]
	s_branch .Lapa4_1933
.Lapa4_1933:
	v_exp_f32_e32 v10, v18
	v_exp_f32_e32 v11, v19
	v_exp_f32_e32 v12, v20
	v_exp_f32_e32 v13, v21
	v_exp_f32_e32 v14, v22
	v_add_f32_e32 v10, 0, v10
	v_exp_f32_e32 v15, v23
	v_add_f32_e32 v10, v11, v10
	v_exp_f32_e32 v16, v24
	v_add_f32_e32 v10, v12, v10
	v_exp_f32_e32 v17, v25
	v_add_f32_e32 v10, v13, v10
	v_exp_f32_e32 v18, v26
	v_add_f32_e32 v10, v14, v10
	v_exp_f32_e32 v19, v27
	v_add_f32_e32 v10, v15, v10
	v_exp_f32_e32 v20, v28
	v_add_f32_e32 v10, v16, v10
	v_exp_f32_e32 v21, v29
	v_add_f32_e32 v10, v17, v10
	v_exp_f32_e32 v22, v30
	v_add_f32_e32 v10, v18, v10
	v_exp_f32_e32 v23, v31
	v_add_f32_e32 v10, v19, v10
	v_exp_f32_e32 v24, v32
	v_add_f32_e32 v10, v20, v10
	v_exp_f32_e32 v25, v33
	v_add_f32_e32 v10, v21, v10
	v_add_f32_e32 v10, v22, v10
	v_exp_f32_e32 v11, v52
	v_add_f32_e32 v10, v23, v10
	v_exp_f32_e32 v12, v53
	v_add_f32_e32 v10, v24, v10
	v_exp_f32_e32 v13, v50
	v_add_f32_e32 v10, v25, v10
	v_exp_f32_e32 v14, v51
	v_add_f32_e32 v10, v10, v11
	v_exp_f32_e32 v11, v48
	v_add_f32_e32 v10, v12, v10
	v_exp_f32_e32 v12, v49
	v_add_f32_e32 v10, v13, v10
	v_exp_f32_e32 v13, v46
	v_add_f32_e32 v10, v14, v10
	v_exp_f32_e32 v14, v47
	v_add_f32_e32 v10, v11, v10
	v_exp_f32_e32 v8, v8
	v_add_f32_e32 v10, v12, v10
	v_exp_f32_e32 v9, v9
	v_add_f32_e32 v10, v13, v10
	v_exp_f32_e32 v6, v6
	v_add_f32_e32 v10, v14, v10
	v_exp_f32_e32 v7, v7
	v_add_f32_e32 v8, v8, v10
	v_exp_f32_e32 v2, v2
	v_add_f32_e32 v8, v9, v8
	v_exp_f32_e32 v3, v3
	v_add_f32_e32 v6, v6, v8
	v_exp_f32_e32 v4, v4
	v_add_f32_e32 v6, v7, v6
	v_exp_f32_e32 v5, v5
	v_add_f32_e32 v2, v2, v6
	v_add_f32_e32 v2, v3, v2
	v_add_f32_e32 v2, v4, v2
	s_add_i32 s31, s31, 1
	v_add_f32_e32 v2, v5, v2
	s_add_i32 s20, s28, s31
	v_add_f32_e32 v54, v54, v2
	v_subrev_u32_e32 v55, 64, v55
	v_lshl_add_u64 v[42:43], v[42:43], 0, s[40:41]
	s_cmp_lg_u32 s20, 2
	v_lshl_add_u64 v[44:45], v[44:45], 0, s[40:41]
	s_barrier
	s_cbranch_scc0 .LBB0_1942
.Lapa5_1934:
	s_add_i32 s20, s31, -2
	s_and_b32 s20, s20, 1
	s_add_i32 s21, s31, -1
	s_cmp_ge_u32 s21, s29
	s_cbranch_scc1 .Lapa5_1936
	s_xor_b32 s21, s20, 1
	s_mulk_i32 s21, 0x4800
	v_or_b32_e32 v2, s21, v111
	v_lshl_add_u32 v3, v154, 1, v2
	v_lshl_add_u32 v2, v152, 1, v2
	s_waitcnt vmcnt(3)
	ds_write_b128 v2, v[216:219]
	s_waitcnt vmcnt(2)
	ds_write_b128 v3, v[220:223]
.Lapa5_1936:
	s_cmp_ge_u32 s31, s29
	s_cbranch_scc1 .Lapa5_1938
.Lapa5_1938:
	s_mulk_i32 s20, 0x4800
	v_add_u32_e32 v50, s20, v156
	ds_read_b128 v[2:5], v50
	ds_read_b128 v[6:9], v50 offset:32
	s_waitcnt lgkmcnt(1)
	v_mfma_f32_32x32x16_bf16 v[18:33], v[2:5], v[78:81], 0
	s_waitcnt lgkmcnt(0)
	v_mfma_f32_32x32x16_bf16 v[18:33], v[6:9], v[66:69], v[18:33]
	ds_read_b128 v[2:5], v50 offset:64
	ds_read_b128 v[6:9], v50 offset:96
	s_waitcnt lgkmcnt(1)
	v_mfma_f32_32x32x16_bf16 v[18:33], v[2:5], v[70:73], v[18:33]
	ds_read_b128 v[2:5], v50 offset:4608
	ds_read_b128 v[46:49], v50 offset:4640
	s_waitcnt lgkmcnt(2)
	v_mfma_f32_32x32x16_bf16 v[18:33], v[6:9], v[74:77], v[18:33]
	s_waitcnt lgkmcnt(1)
	v_mfma_f32_32x32x16_bf16 v[2:17], v[2:5], v[78:81], 0
	s_waitcnt lgkmcnt(0)
	v_mfma_f32_32x32x16_bf16 v[2:17], v[46:49], v[66:69], v[2:17]
	ds_read_b128 v[46:49], v50 offset:4672
	ds_read_b128 v[50:53], v50 offset:4704
	s_waitcnt lgkmcnt(1)
	v_mfma_f32_32x32x16_bf16 v[2:17], v[46:49], v[70:73], v[2:17]
	s_waitcnt lgkmcnt(0)
	v_mfma_f32_32x32x16_bf16 v[2:17], v[50:53], v[74:77], v[2:17]
	v_cmp_lt_i32_e32 vcc, 26, v55
	s_nop 0
	v_fma_f32 v18, v18, s48, v100
	v_fma_f32 v19, v19, s48, v101
	v_fma_f32 v20, v20, s48, v100
	v_fma_f32 v21, v21, s48, v101
	v_pk_fma_f32 v[22:23], v[22:23], s[48:49], v[100:101] op_sel_hi:[1,0,1]
	v_pk_fma_f32 v[24:25], v[24:25], s[48:49], v[100:101] op_sel_hi:[1,0,1]
	v_pk_fma_f32 v[26:27], v[26:27], s[48:49], v[100:101] op_sel_hi:[1,0,1]
	v_pk_fma_f32 v[28:29], v[28:29], s[48:49], v[100:101] op_sel_hi:[1,0,1]
	v_pk_fma_f32 v[30:31], v[30:31], s[48:49], v[100:101] op_sel_hi:[1,0,1]
	s_cmp_eq_u64 vcc, exec
	v_pk_fma_f32 v[32:33], v[32:33], s[48:49], v[100:101] op_sel_hi:[1,0,1]
	s_cbranch_scc1 .Lapa5_1940
	v_cmp_lt_i32_e64 s[20:21], -1, v55
	v_cndmask_b32_e32 v33, v213, v33, vcc
	s_nop 0
	v_cndmask_b32_e64 v18, v213, v18, s[20:21]
	v_cmp_lt_i32_e64 s[20:21], 0, v55
	s_nop 1
	v_cndmask_b32_e64 v19, v213, v19, s[20:21]
	v_cmp_lt_i32_e64 s[20:21], 1, v55
	s_nop 1
	v_cndmask_b32_e64 v20, v213, v20, s[20:21]
	v_cmp_lt_i32_e64 s[20:21], 2, v55
	s_nop 1
	v_cndmask_b32_e64 v21, v213, v21, s[20:21]
	v_cmp_lt_i32_e64 s[20:21], 7, v55
	s_nop 1
	v_cndmask_b32_e64 v22, v213, v22, s[20:21]
	v_cmp_lt_i32_e64 s[20:21], 8, v55
	s_nop 1
	v_cndmask_b32_e64 v23, v213, v23, s[20:21]
	v_cmp_lt_i32_e64 s[20:21], 9, v55
	s_nop 1
	v_cndmask_b32_e64 v24, v213, v24, s[20:21]
	v_cmp_lt_i32_e64 s[20:21], 10, v55
	s_nop 1
	v_cndmask_b32_e64 v25, v213, v25, s[20:21]
	v_cmp_lt_i32_e64 s[20:21], 15, v55
	s_nop 1
	v_cndmask_b32_e64 v26, v213, v26, s[20:21]
	v_cmp_lt_i32_e64 s[20:21], 16, v55
	s_nop 1
	v_cndmask_b32_e64 v27, v213, v27, s[20:21]
	v_cmp_lt_i32_e64 s[20:21], 17, v55
	s_nop 1
	v_cndmask_b32_e64 v28, v213, v28, s[20:21]
	v_cmp_lt_i32_e64 s[20:21], 18, v55
	s_nop 1
	v_cndmask_b32_e64 v29, v213, v29, s[20:21]
	v_cmp_lt_i32_e64 s[20:21], 23, v55
	s_nop 1
	v_cndmask_b32_e64 v30, v213, v30, s[20:21]
	v_cmp_lt_i32_e64 s[20:21], 24, v55
	s_nop 1
	v_cndmask_b32_e64 v31, v213, v31, s[20:21]
	v_cmp_lt_i32_e64 s[20:21], 25, v55
	s_nop 1
	v_cndmask_b32_e64 v32, v213, v32, s[20:21]
.Lapa5_1940:
	v_subrev_u32_e32 v56, 32, v55
	v_cmp_lt_i32_e32 vcc, 26, v56
	v_pk_fma_f32 v[52:53], v[2:3], s[48:49], v[100:101] op_sel_hi:[1,0,1]
	v_pk_fma_f32 v[50:51], v[4:5], s[48:49], v[100:101] op_sel_hi:[1,0,1]
	v_pk_fma_f32 v[48:49], v[6:7], s[48:49], v[100:101] op_sel_hi:[1,0,1]
	v_pk_fma_f32 v[46:47], v[8:9], s[48:49], v[100:101] op_sel_hi:[1,0,1]
	v_pk_fma_f32 v[8:9], v[10:11], s[48:49], v[100:101] op_sel_hi:[1,0,1]
	v_pk_fma_f32 v[6:7], v[12:13], s[48:49], v[100:101] op_sel_hi:[1,0,1]
	v_pk_fma_f32 v[2:3], v[14:15], s[48:49], v[100:101] op_sel_hi:[1,0,1]
	s_cmp_eq_u64 vcc, exec
	v_pk_fma_f32 v[4:5], v[16:17], s[48:49], v[100:101] op_sel_hi:[1,0,1]
	s_cbranch_scc1 .Lapa5_1933
	v_cmp_lt_i32_e64 s[20:21], -1, v56
	v_cndmask_b32_e32 v5, v213, v5, vcc
	s_nop 0
	v_cndmask_b32_e64 v52, v213, v52, s[20:21]
	v_cmp_lt_i32_e64 s[20:21], 0, v56
	s_nop 1
	v_cndmask_b32_e64 v53, v213, v53, s[20:21]
	v_cmp_lt_i32_e64 s[20:21], 1, v56
	s_nop 1
	v_cndmask_b32_e64 v50, v213, v50, s[20:21]
	v_cmp_lt_i32_e64 s[20:21], 2, v56
	s_nop 1
	v_cndmask_b32_e64 v51, v213, v51, s[20:21]
	v_cmp_lt_i32_e64 s[20:21], 7, v56
	s_nop 1
	v_cndmask_b32_e64 v48, v213, v48, s[20:21]
	v_cmp_lt_i32_e64 s[20:21], 8, v56
	s_nop 1
	v_cndmask_b32_e64 v49, v213, v49, s[20:21]
	v_cmp_lt_i32_e64 s[20:21], 9, v56
	s_nop 1
	v_cndmask_b32_e64 v46, v213, v46, s[20:21]
	v_cmp_lt_i32_e64 s[20:21], 10, v56
	s_nop 1
	v_cndmask_b32_e64 v47, v213, v47, s[20:21]
	v_cmp_lt_i32_e64 s[20:21], 15, v56
	s_nop 1
	v_cndmask_b32_e64 v8, v213, v8, s[20:21]
	v_cmp_lt_i32_e64 s[20:21], 16, v56
	s_nop 1
	v_cndmask_b32_e64 v9, v213, v9, s[20:21]
	v_cmp_lt_i32_e64 s[20:21], 17, v56
	s_nop 1
	v_cndmask_b32_e64 v6, v213, v6, s[20:21]
	v_cmp_lt_i32_e64 s[20:21], 18, v56
	s_nop 1
	v_cndmask_b32_e64 v7, v213, v7, s[20:21]
	v_cmp_lt_i32_e64 s[20:21], 23, v56
	s_nop 1
	v_cndmask_b32_e64 v2, v213, v2, s[20:21]
	v_cmp_lt_i32_e64 s[20:21], 24, v56
	s_nop 1
	v_cndmask_b32_e64 v3, v213, v3, s[20:21]
	v_cmp_lt_i32_e64 s[20:21], 25, v56
	s_nop 1
	v_cndmask_b32_e64 v4, v213, v4, s[20:21]
	s_branch .Lapa5_1933
.Lapa5_1933:
	v_exp_f32_e32 v10, v18
	v_exp_f32_e32 v11, v19
	v_exp_f32_e32 v12, v20
	v_exp_f32_e32 v13, v21
	v_exp_f32_e32 v14, v22
	v_add_f32_e32 v10, 0, v10
	v_exp_f32_e32 v15, v23
	v_add_f32_e32 v10, v11, v10
	v_exp_f32_e32 v16, v24
	v_add_f32_e32 v10, v12, v10
	v_exp_f32_e32 v17, v25
	v_add_f32_e32 v10, v13, v10
	v_exp_f32_e32 v18, v26
	v_add_f32_e32 v10, v14, v10
	v_exp_f32_e32 v19, v27
	v_add_f32_e32 v10, v15, v10
	v_exp_f32_e32 v20, v28
	v_add_f32_e32 v10, v16, v10
	v_exp_f32_e32 v21, v29
	v_add_f32_e32 v10, v17, v10
	v_exp_f32_e32 v22, v30
	v_add_f32_e32 v10, v18, v10
	v_exp_f32_e32 v23, v31
	v_add_f32_e32 v10, v19, v10
	v_exp_f32_e32 v24, v32
	v_add_f32_e32 v10, v20, v10
	v_exp_f32_e32 v25, v33
	v_add_f32_e32 v10, v21, v10
	v_add_f32_e32 v10, v22, v10
	v_exp_f32_e32 v11, v52
	v_add_f32_e32 v10, v23, v10
	v_exp_f32_e32 v12, v53
	v_add_f32_e32 v10, v24, v10
	v_exp_f32_e32 v13, v50
	v_add_f32_e32 v10, v25, v10
	v_exp_f32_e32 v14, v51
	v_add_f32_e32 v10, v10, v11
	v_exp_f32_e32 v11, v48
	v_add_f32_e32 v10, v12, v10
	v_exp_f32_e32 v12, v49
	v_add_f32_e32 v10, v13, v10
	v_exp_f32_e32 v13, v46
	v_add_f32_e32 v10, v14, v10
	v_exp_f32_e32 v14, v47
	v_add_f32_e32 v10, v11, v10
	v_exp_f32_e32 v8, v8
	v_add_f32_e32 v10, v12, v10
	v_exp_f32_e32 v9, v9
	v_add_f32_e32 v10, v13, v10
	v_exp_f32_e32 v6, v6
	v_add_f32_e32 v10, v14, v10
	v_exp_f32_e32 v7, v7
	v_add_f32_e32 v8, v8, v10
	v_exp_f32_e32 v2, v2
	v_add_f32_e32 v8, v9, v8
	v_exp_f32_e32 v3, v3
	v_add_f32_e32 v6, v6, v8
	v_exp_f32_e32 v4, v4
	v_add_f32_e32 v6, v7, v6
	v_exp_f32_e32 v5, v5
	v_add_f32_e32 v2, v2, v6
	v_add_f32_e32 v2, v3, v2
	v_add_f32_e32 v2, v4, v2
	s_add_i32 s31, s31, 1
	v_add_f32_e32 v2, v5, v2
	s_add_i32 s20, s28, s31
	v_add_f32_e32 v54, v54, v2
	v_subrev_u32_e32 v55, 64, v55
	v_lshl_add_u64 v[42:43], v[42:43], 0, s[40:41]
	s_cmp_lg_u32 s20, 2
	v_lshl_add_u64 v[44:45], v[44:45], 0, s[40:41]
	s_barrier
	s_cbranch_scc0 .LBB0_1942
.Lapa6_1934:
	s_add_i32 s20, s31, -2
	s_and_b32 s20, s20, 1
	s_add_i32 s21, s31, -1
	s_cmp_ge_u32 s21, s29
	s_cbranch_scc1 .Lapa6_1936
	s_xor_b32 s21, s20, 1
	s_mulk_i32 s21, 0x4800
	v_or_b32_e32 v2, s21, v111
	v_lshl_add_u32 v3, v154, 1, v2
	v_lshl_add_u32 v2, v152, 1, v2
	s_waitcnt vmcnt(1)
	ds_write_b128 v2, v[224:227]
	s_waitcnt vmcnt(0)
	ds_write_b128 v3, v[234:237]
.Lapa6_1936:
	s_cmp_ge_u32 s31, s29
	s_cbranch_scc1 .Lapa6_1938
.Lapa6_1938:
	s_mulk_i32 s20, 0x4800
	v_add_u32_e32 v50, s20, v156
	ds_read_b128 v[2:5], v50
	ds_read_b128 v[6:9], v50 offset:32
	s_waitcnt lgkmcnt(1)
	v_mfma_f32_32x32x16_bf16 v[18:33], v[2:5], v[78:81], 0
	s_waitcnt lgkmcnt(0)
	v_mfma_f32_32x32x16_bf16 v[18:33], v[6:9], v[66:69], v[18:33]
	ds_read_b128 v[2:5], v50 offset:64
	ds_read_b128 v[6:9], v50 offset:96
	s_waitcnt lgkmcnt(1)
	v_mfma_f32_32x32x16_bf16 v[18:33], v[2:5], v[70:73], v[18:33]
	ds_read_b128 v[2:5], v50 offset:4608
	ds_read_b128 v[46:49], v50 offset:4640
	s_waitcnt lgkmcnt(2)
	v_mfma_f32_32x32x16_bf16 v[18:33], v[6:9], v[74:77], v[18:33]
	s_waitcnt lgkmcnt(1)
	v_mfma_f32_32x32x16_bf16 v[2:17], v[2:5], v[78:81], 0
	s_waitcnt lgkmcnt(0)
	v_mfma_f32_32x32x16_bf16 v[2:17], v[46:49], v[66:69], v[2:17]
	ds_read_b128 v[46:49], v50 offset:4672
	ds_read_b128 v[50:53], v50 offset:4704
	s_waitcnt lgkmcnt(1)
	v_mfma_f32_32x32x16_bf16 v[2:17], v[46:49], v[70:73], v[2:17]
	s_waitcnt lgkmcnt(0)
	v_mfma_f32_32x32x16_bf16 v[2:17], v[50:53], v[74:77], v[2:17]
	v_cmp_lt_i32_e32 vcc, 26, v55
	s_nop 0
	v_fma_f32 v18, v18, s48, v100
	v_fma_f32 v19, v19, s48, v101
	v_fma_f32 v20, v20, s48, v100
	v_fma_f32 v21, v21, s48, v101
	v_pk_fma_f32 v[22:23], v[22:23], s[48:49], v[100:101] op_sel_hi:[1,0,1]
	v_pk_fma_f32 v[24:25], v[24:25], s[48:49], v[100:101] op_sel_hi:[1,0,1]
	v_pk_fma_f32 v[26:27], v[26:27], s[48:49], v[100:101] op_sel_hi:[1,0,1]
	v_pk_fma_f32 v[28:29], v[28:29], s[48:49], v[100:101] op_sel_hi:[1,0,1]
	v_pk_fma_f32 v[30:31], v[30:31], s[48:49], v[100:101] op_sel_hi:[1,0,1]
	s_cmp_eq_u64 vcc, exec
	v_pk_fma_f32 v[32:33], v[32:33], s[48:49], v[100:101] op_sel_hi:[1,0,1]
	s_cbranch_scc1 .Lapa6_1940
	v_cmp_lt_i32_e64 s[20:21], -1, v55
	v_cndmask_b32_e32 v33, v213, v33, vcc
	s_nop 0
	v_cndmask_b32_e64 v18, v213, v18, s[20:21]
	v_cmp_lt_i32_e64 s[20:21], 0, v55
	s_nop 1
	v_cndmask_b32_e64 v19, v213, v19, s[20:21]
	v_cmp_lt_i32_e64 s[20:21], 1, v55
	s_nop 1
	v_cndmask_b32_e64 v20, v213, v20, s[20:21]
	v_cmp_lt_i32_e64 s[20:21], 2, v55
	s_nop 1
	v_cndmask_b32_e64 v21, v213, v21, s[20:21]
	v_cmp_lt_i32_e64 s[20:21], 7, v55
	s_nop 1
	v_cndmask_b32_e64 v22, v213, v22, s[20:21]
	v_cmp_lt_i32_e64 s[20:21], 8, v55
	s_nop 1
	v_cndmask_b32_e64 v23, v213, v23, s[20:21]
	v_cmp_lt_i32_e64 s[20:21], 9, v55
	s_nop 1
	v_cndmask_b32_e64 v24, v213, v24, s[20:21]
	v_cmp_lt_i32_e64 s[20:21], 10, v55
	s_nop 1
	v_cndmask_b32_e64 v25, v213, v25, s[20:21]
	v_cmp_lt_i32_e64 s[20:21], 15, v55
	s_nop 1
	v_cndmask_b32_e64 v26, v213, v26, s[20:21]
	v_cmp_lt_i32_e64 s[20:21], 16, v55
	s_nop 1
	v_cndmask_b32_e64 v27, v213, v27, s[20:21]
	v_cmp_lt_i32_e64 s[20:21], 17, v55
	s_nop 1
	v_cndmask_b32_e64 v28, v213, v28, s[20:21]
	v_cmp_lt_i32_e64 s[20:21], 18, v55
	s_nop 1
	v_cndmask_b32_e64 v29, v213, v29, s[20:21]
	v_cmp_lt_i32_e64 s[20:21], 23, v55
	s_nop 1
	v_cndmask_b32_e64 v30, v213, v30, s[20:21]
	v_cmp_lt_i32_e64 s[20:21], 24, v55
	s_nop 1
	v_cndmask_b32_e64 v31, v213, v31, s[20:21]
	v_cmp_lt_i32_e64 s[20:21], 25, v55
	s_nop 1
	v_cndmask_b32_e64 v32, v213, v32, s[20:21]
.Lapa6_1940:
	v_subrev_u32_e32 v56, 32, v55
	v_cmp_lt_i32_e32 vcc, 26, v56
	v_pk_fma_f32 v[52:53], v[2:3], s[48:49], v[100:101] op_sel_hi:[1,0,1]
	v_pk_fma_f32 v[50:51], v[4:5], s[48:49], v[100:101] op_sel_hi:[1,0,1]
	v_pk_fma_f32 v[48:49], v[6:7], s[48:49], v[100:101] op_sel_hi:[1,0,1]
	v_pk_fma_f32 v[46:47], v[8:9], s[48:49], v[100:101] op_sel_hi:[1,0,1]
	v_pk_fma_f32 v[8:9], v[10:11], s[48:49], v[100:101] op_sel_hi:[1,0,1]
	v_pk_fma_f32 v[6:7], v[12:13], s[48:49], v[100:101] op_sel_hi:[1,0,1]
	v_pk_fma_f32 v[2:3], v[14:15], s[48:49], v[100:101] op_sel_hi:[1,0,1]
	s_cmp_eq_u64 vcc, exec
	v_pk_fma_f32 v[4:5], v[16:17], s[48:49], v[100:101] op_sel_hi:[1,0,1]
	s_cbranch_scc1 .Lapa6_1933
	v_cmp_lt_i32_e64 s[20:21], -1, v56
	v_cndmask_b32_e32 v5, v213, v5, vcc
	s_nop 0
	v_cndmask_b32_e64 v52, v213, v52, s[20:21]
	v_cmp_lt_i32_e64 s[20:21], 0, v56
	s_nop 1
	v_cndmask_b32_e64 v53, v213, v53, s[20:21]
	v_cmp_lt_i32_e64 s[20:21], 1, v56
	s_nop 1
	v_cndmask_b32_e64 v50, v213, v50, s[20:21]
	v_cmp_lt_i32_e64 s[20:21], 2, v56
	s_nop 1
	v_cndmask_b32_e64 v51, v213, v51, s[20:21]
	v_cmp_lt_i32_e64 s[20:21], 7, v56
	s_nop 1
	v_cndmask_b32_e64 v48, v213, v48, s[20:21]
	v_cmp_lt_i32_e64 s[20:21], 8, v56
	s_nop 1
	v_cndmask_b32_e64 v49, v213, v49, s[20:21]
	v_cmp_lt_i32_e64 s[20:21], 9, v56
	s_nop 1
	v_cndmask_b32_e64 v46, v213, v46, s[20:21]
	v_cmp_lt_i32_e64 s[20:21], 10, v56
	s_nop 1
	v_cndmask_b32_e64 v47, v213, v47, s[20:21]
	v_cmp_lt_i32_e64 s[20:21], 15, v56
	s_nop 1
	v_cndmask_b32_e64 v8, v213, v8, s[20:21]
	v_cmp_lt_i32_e64 s[20:21], 16, v56
	s_nop 1
	v_cndmask_b32_e64 v9, v213, v9, s[20:21]
	v_cmp_lt_i32_e64 s[20:21], 17, v56
	s_nop 1
	v_cndmask_b32_e64 v6, v213, v6, s[20:21]
	v_cmp_lt_i32_e64 s[20:21], 18, v56
	s_nop 1
	v_cndmask_b32_e64 v7, v213, v7, s[20:21]
	v_cmp_lt_i32_e64 s[20:21], 23, v56
	s_nop 1
	v_cndmask_b32_e64 v2, v213, v2, s[20:21]
	v_cmp_lt_i32_e64 s[20:21], 24, v56
	s_nop 1
	v_cndmask_b32_e64 v3, v213, v3, s[20:21]
	v_cmp_lt_i32_e64 s[20:21], 25, v56
	s_nop 1
	v_cndmask_b32_e64 v4, v213, v4, s[20:21]
	s_branch .Lapa6_1933
.Lapa6_1933:
	v_exp_f32_e32 v10, v18
	v_exp_f32_e32 v11, v19
	v_exp_f32_e32 v12, v20
	v_exp_f32_e32 v13, v21
	v_exp_f32_e32 v14, v22
	v_add_f32_e32 v10, 0, v10
	v_exp_f32_e32 v15, v23
	v_add_f32_e32 v10, v11, v10
	v_exp_f32_e32 v16, v24
	v_add_f32_e32 v10, v12, v10
	v_exp_f32_e32 v17, v25
	v_add_f32_e32 v10, v13, v10
	v_exp_f32_e32 v18, v26
	v_add_f32_e32 v10, v14, v10
	v_exp_f32_e32 v19, v27
	v_add_f32_e32 v10, v15, v10
	v_exp_f32_e32 v20, v28
	v_add_f32_e32 v10, v16, v10
	v_exp_f32_e32 v21, v29
	v_add_f32_e32 v10, v17, v10
	v_exp_f32_e32 v22, v30
	v_add_f32_e32 v10, v18, v10
	v_exp_f32_e32 v23, v31
	v_add_f32_e32 v10, v19, v10
	v_exp_f32_e32 v24, v32
	v_add_f32_e32 v10, v20, v10
	v_exp_f32_e32 v25, v33
	v_add_f32_e32 v10, v21, v10
	v_add_f32_e32 v10, v22, v10
	v_exp_f32_e32 v11, v52
	v_add_f32_e32 v10, v23, v10
	v_exp_f32_e32 v12, v53
	v_add_f32_e32 v10, v24, v10
	v_exp_f32_e32 v13, v50
	v_add_f32_e32 v10, v25, v10
	v_exp_f32_e32 v14, v51
	v_add_f32_e32 v10, v10, v11
	v_exp_f32_e32 v11, v48
	v_add_f32_e32 v10, v12, v10
	v_exp_f32_e32 v12, v49
	v_add_f32_e32 v10, v13, v10
	v_exp_f32_e32 v13, v46
	v_add_f32_e32 v10, v14, v10
	v_exp_f32_e32 v14, v47
	v_add_f32_e32 v10, v11, v10
	v_exp_f32_e32 v8, v8
	v_add_f32_e32 v10, v12, v10
	v_exp_f32_e32 v9, v9
	v_add_f32_e32 v10, v13, v10
	v_exp_f32_e32 v6, v6
	v_add_f32_e32 v10, v14, v10
	v_exp_f32_e32 v7, v7
	v_add_f32_e32 v8, v8, v10
	v_exp_f32_e32 v2, v2
	v_add_f32_e32 v8, v9, v8
	v_exp_f32_e32 v3, v3
	v_add_f32_e32 v6, v6, v8
	v_exp_f32_e32 v4, v4
	v_add_f32_e32 v6, v7, v6
	v_exp_f32_e32 v5, v5
	v_add_f32_e32 v2, v2, v6
	v_add_f32_e32 v2, v3, v2
	v_add_f32_e32 v2, v4, v2
	s_add_i32 s31, s31, 1
	v_add_f32_e32 v2, v5, v2
	s_add_i32 s20, s28, s31
	v_add_f32_e32 v54, v54, v2
	v_subrev_u32_e32 v55, 64, v55
	v_lshl_add_u64 v[42:43], v[42:43], 0, s[40:41]
	s_cmp_lg_u32 s20, 2
	v_lshl_add_u64 v[44:45], v[44:45], 0, s[40:41]
	s_barrier
	s_cbranch_scc0 .LBB0_1942
.Lapa7_1934:
	s_add_i32 s20, s31, -2
	s_and_b32 s20, s20, 1
	s_add_i32 s21, s31, -1
	s_cmp_ge_u32 s21, s29
	s_cbranch_scc1 .Lapa7_1936
	s_xor_b32 s21, s20, 1
	s_mulk_i32 s21, 0x4800
	v_or_b32_e32 v2, s21, v111
	v_lshl_add_u32 v3, v154, 1, v2
	v_lshl_add_u32 v2, v152, 1, v2
	s_waitcnt vmcnt(1)
	ds_write_b128 v2, v[58:61]
	s_waitcnt vmcnt(0)
	ds_write_b128 v3, v[62:65]
.Lapa7_1936:
	s_cmp_ge_u32 s31, s29
	s_cbranch_scc1 .Lapa7_1938
.Lapa7_1938:
	s_mulk_i32 s20, 0x4800
	v_add_u32_e32 v50, s20, v156
	ds_read_b128 v[2:5], v50
	ds_read_b128 v[6:9], v50 offset:32
	s_waitcnt lgkmcnt(1)
	v_mfma_f32_32x32x16_bf16 v[18:33], v[2:5], v[78:81], 0
	s_waitcnt lgkmcnt(0)
	v_mfma_f32_32x32x16_bf16 v[18:33], v[6:9], v[66:69], v[18:33]
	ds_read_b128 v[2:5], v50 offset:64
	ds_read_b128 v[6:9], v50 offset:96
	s_waitcnt lgkmcnt(1)
	v_mfma_f32_32x32x16_bf16 v[18:33], v[2:5], v[70:73], v[18:33]
	ds_read_b128 v[2:5], v50 offset:4608
	ds_read_b128 v[46:49], v50 offset:4640
	s_waitcnt lgkmcnt(2)
	v_mfma_f32_32x32x16_bf16 v[18:33], v[6:9], v[74:77], v[18:33]
	s_waitcnt lgkmcnt(1)
	v_mfma_f32_32x32x16_bf16 v[2:17], v[2:5], v[78:81], 0
	s_waitcnt lgkmcnt(0)
	v_mfma_f32_32x32x16_bf16 v[2:17], v[46:49], v[66:69], v[2:17]
	ds_read_b128 v[46:49], v50 offset:4672
	ds_read_b128 v[50:53], v50 offset:4704
	s_waitcnt lgkmcnt(1)
	v_mfma_f32_32x32x16_bf16 v[2:17], v[46:49], v[70:73], v[2:17]
	s_waitcnt lgkmcnt(0)
	v_mfma_f32_32x32x16_bf16 v[2:17], v[50:53], v[74:77], v[2:17]
	v_cmp_lt_i32_e32 vcc, 26, v55
	s_nop 0
	v_fma_f32 v18, v18, s48, v100
	v_fma_f32 v19, v19, s48, v101
	v_fma_f32 v20, v20, s48, v100
	v_fma_f32 v21, v21, s48, v101
	v_pk_fma_f32 v[22:23], v[22:23], s[48:49], v[100:101] op_sel_hi:[1,0,1]
	v_pk_fma_f32 v[24:25], v[24:25], s[48:49], v[100:101] op_sel_hi:[1,0,1]
	v_pk_fma_f32 v[26:27], v[26:27], s[48:49], v[100:101] op_sel_hi:[1,0,1]
	v_pk_fma_f32 v[28:29], v[28:29], s[48:49], v[100:101] op_sel_hi:[1,0,1]
	v_pk_fma_f32 v[30:31], v[30:31], s[48:49], v[100:101] op_sel_hi:[1,0,1]
	s_cmp_eq_u64 vcc, exec
	v_pk_fma_f32 v[32:33], v[32:33], s[48:49], v[100:101] op_sel_hi:[1,0,1]
	s_cbranch_scc1 .Lapa7_1940
	v_cmp_lt_i32_e64 s[20:21], -1, v55
	v_cndmask_b32_e32 v33, v213, v33, vcc
	s_nop 0
	v_cndmask_b32_e64 v18, v213, v18, s[20:21]
	v_cmp_lt_i32_e64 s[20:21], 0, v55
	s_nop 1
	v_cndmask_b32_e64 v19, v213, v19, s[20:21]
	v_cmp_lt_i32_e64 s[20:21], 1, v55
	s_nop 1
	v_cndmask_b32_e64 v20, v213, v20, s[20:21]
	v_cmp_lt_i32_e64 s[20:21], 2, v55
	s_nop 1
	v_cndmask_b32_e64 v21, v213, v21, s[20:21]
	v_cmp_lt_i32_e64 s[20:21], 7, v55
	s_nop 1
	v_cndmask_b32_e64 v22, v213, v22, s[20:21]
	v_cmp_lt_i32_e64 s[20:21], 8, v55
	s_nop 1
	v_cndmask_b32_e64 v23, v213, v23, s[20:21]
	v_cmp_lt_i32_e64 s[20:21], 9, v55
	s_nop 1
	v_cndmask_b32_e64 v24, v213, v24, s[20:21]
	v_cmp_lt_i32_e64 s[20:21], 10, v55
	s_nop 1
	v_cndmask_b32_e64 v25, v213, v25, s[20:21]
	v_cmp_lt_i32_e64 s[20:21], 15, v55
	s_nop 1
	v_cndmask_b32_e64 v26, v213, v26, s[20:21]
	v_cmp_lt_i32_e64 s[20:21], 16, v55
	s_nop 1
	v_cndmask_b32_e64 v27, v213, v27, s[20:21]
	v_cmp_lt_i32_e64 s[20:21], 17, v55
	s_nop 1
	v_cndmask_b32_e64 v28, v213, v28, s[20:21]
	v_cmp_lt_i32_e64 s[20:21], 18, v55
	s_nop 1
	v_cndmask_b32_e64 v29, v213, v29, s[20:21]
	v_cmp_lt_i32_e64 s[20:21], 23, v55
	s_nop 1
	v_cndmask_b32_e64 v30, v213, v30, s[20:21]
	v_cmp_lt_i32_e64 s[20:21], 24, v55
	s_nop 1
	v_cndmask_b32_e64 v31, v213, v31, s[20:21]
	v_cmp_lt_i32_e64 s[20:21], 25, v55
	s_nop 1
	v_cndmask_b32_e64 v32, v213, v32, s[20:21]

.Lapa7_1933:
	v_exp_f32_e32 v10, v18
	v_exp_f32_e32 v11, v19
	v_exp_f32_e32 v12, v20
	v_exp_f32_e32 v13, v21
	v_exp_f32_e32 v14, v22
	v_add_f32_e32 v10, 0, v10
	v_exp_f32_e32 v15, v23
	v_add_f32_e32 v10, v11, v10
	v_exp_f32_e32 v16, v24
	v_add_f32_e32 v10, v12, v10
	v_exp_f32_e32 v17, v25
	v_add_f32_e32 v10, v13, v10
	v_exp_f32_e32 v18, v26
	v_add_f32_e32 v10, v14, v10
	v_exp_f32_e32 v19, v27
	v_add_f32_e32 v10, v15, v10
	v_exp_f32_e32 v20, v28
	v_add_f32_e32 v10, v16, v10
	v_exp_f32_e32 v21, v29
	v_add_f32_e32 v10, v17, v10
	v_exp_f32_e32 v22, v30
	v_add_f32_e32 v10, v18, v10
	v_exp_f32_e32 v23, v31
	v_add_f32_e32 v10, v19, v10
	v_exp_f32_e32 v24, v32
	v_add_f32_e32 v10, v20, v10
	v_exp_f32_e32 v25, v33
	v_add_f32_e32 v10, v21, v10
	v_add_f32_e32 v10, v22, v10
	v_exp_f32_e32 v11, v52
	v_add_f32_e32 v10, v23, v10
	v_exp_f32_e32 v12, v53
	v_add_f32_e32 v10, v24, v10
	v_exp_f32_e32 v13, v50
	v_add_f32_e32 v10, v25, v10
	v_exp_f32_e32 v14, v51
	v_add_f32_e32 v10, v10, v11
	v_exp_f32_e32 v11, v48
	v_add_f32_e32 v10, v12, v10
	v_exp_f32_e32 v12, v49
	v_add_f32_e32 v10, v13, v10
	v_exp_f32_e32 v13, v46
	v_add_f32_e32 v10, v14, v10
	v_exp_f32_e32 v14, v47
	v_add_f32_e32 v10, v11, v10
	v_exp_f32_e32 v8, v8
	v_add_f32_e32 v10, v12, v10
	v_exp_f32_e32 v9, v9
	v_add_f32_e32 v10, v13, v10
	v_exp_f32_e32 v6, v6
	v_add_f32_e32 v10, v14, v10
	v_exp_f32_e32 v7, v7
	v_add_f32_e32 v8, v8, v10
	v_exp_f32_e32 v2, v2
	v_add_f32_e32 v8, v9, v8
	v_exp_f32_e32 v3, v3
	v_add_f32_e32 v6, v6, v8
	v_exp_f32_e32 v4, v4
	v_add_f32_e32 v6, v7, v6
	v_exp_f32_e32 v5, v5
	v_add_f32_e32 v2, v2, v6
	v_add_f32_e32 v2, v3, v2
	v_add_f32_e32 v2, v4, v2
	s_add_i32 s31, s31, 1
	v_add_f32_e32 v2, v5, v2
	s_add_i32 s20, s28, s31
	v_add_f32_e32 v54, v54, v2
	v_subrev_u32_e32 v55, 64, v55
	v_lshl_add_u64 v[42:43], v[42:43], 0, s[40:41]
	s_cmp_lg_u32 s20, 2
	v_lshl_add_u64 v[44:45], v[44:45], 0, s[40:41]
	s_barrier
	s_cbranch_scc0 .LBB0_1942
	s_branch .LBB0_1942
.LBB0_1942:
	s_waitcnt vmcnt(0)
	ds_bpermute_b32 v2, v158, v54
	v_mov_b32_e32 v33, 0
	v_mov_b32_e32 v32, v33
	v_mov_b32_e32 v31, v33
	v_mov_b32_e32 v30, v33
	s_waitcnt lgkmcnt(0)
	v_add_f32_e32 v2, v54, v2
	v_div_scale_f32 v3, s[20:21], v2, v2, 1.0
	v_rcp_f32_e32 v4, v3
	v_div_scale_f32 v5, vcc, 1.0, v2, 1.0
	v_mov_b32_e32 v29, v33
	v_fma_f32 v6, -v3, v4, 1.0
	v_fmac_f32_e32 v4, v6, v4
	v_mul_f32_e32 v6, v5, v4
	v_fma_f32 v7, -v3, v6, v5
	v_fmac_f32_e32 v6, v7, v4
	v_fma_f32 v3, -v3, v6, v5
	v_div_fmas_f32 v3, v3, v4, v6
	v_div_fixup_f32 v3, v3, v2, 1.0
	v_cmp_lt_f32_e32 vcc, 0, v2
	v_mov_b32_e32 v28, v33
	v_mov_b32_e32 v27, v33
	v_cndmask_b32_e32 v146, 0, v3, vcc
	s_andn2_b64 vcc, exec, s[24:25]
	v_mov_b32_e32 v26, v33
	v_mov_b32_e32 v25, v33
	v_mov_b32_e32 v24, v33
	v_mov_b32_e32 v23, v33
	v_mov_b32_e32 v22, v33
	v_mov_b32_e32 v21, v33
	v_mov_b32_e32 v20, v33
	v_mov_b32_e32 v19, v33
	v_mov_b32_e32 v18, v33
	v_mov_b32_e32 v17, v33
	v_mov_b32_e32 v16, v33
	v_mov_b32_e32 v15, v33
	v_mov_b32_e32 v14, v33
	v_mov_b32_e32 v13, v33
	v_mov_b32_e32 v12, v33
	v_mov_b32_e32 v11, v33
	v_mov_b32_e32 v10, v33
	v_mov_b32_e32 v9, v33
	v_mov_b32_e32 v8, v33
	v_mov_b32_e32 v7, v33
	v_mov_b32_e32 v6, v33
	v_mov_b32_e32 v5, v33
	v_mov_b32_e32 v4, v33
	v_mov_b32_e32 v3, v33
	v_mov_b32_e32 v2, v33
	s_cbranch_vccnz .LBB0_1971
	v_readlane_b32 s20, v231, 20
	v_readlane_b32 s21, v231, 21
	s_add_u32 s20, s20, s30
	v_mov_b32_e32 v129, v105
	s_addc_u32 s21, s21, 0
	v_lshl_add_u64 v[2:3], s[22:23], 0, v[128:129]
	v_lshl_add_u64 v[6:7], v[2:3], 0, v[106:107]
	v_lshl_add_u64 v[4:5], s[20:21], 0, v[128:129]
	v_lshl_add_u64 v[8:9], v[4:5], 0, v[106:107]
	global_load_dwordx4 v[82:85], v[6:7], off
	global_load_dwordx4 v[86:89], v[8:9], off
	v_lshl_add_u64 v[6:7], v[2:3], 0, v[108:109]
	v_lshl_add_u64 v[8:9], v[4:5], 0, v[108:109]
	global_load_dwordx4 v[90:93], v[6:7], off
	global_load_dwordx4 v[94:97], v[8:9], off
	s_cmp_eq_u32 s29, 1
	s_waitcnt vmcnt(3)
	ds_write_b128 v153, v[82:85]
	s_waitcnt vmcnt(2)
	ds_write_b128 v153, v[86:89] offset:9216
	s_waitcnt vmcnt(1)
	ds_write_b128 v155, v[90:93]
	s_waitcnt vmcnt(0)
	ds_write_b128 v155, v[94:97] offset:9216
	s_cbranch_scc1 .LBB0_1945
	v_lshl_add_u64 v[2:3], v[2:3], 0, s[40:41]
	v_lshl_add_u64 v[6:7], v[2:3], 0, v[106:107]
	v_lshl_add_u64 v[4:5], v[4:5], 0, s[40:41]
	v_lshl_add_u64 v[2:3], v[2:3], 0, v[108:109]
	v_lshl_add_u64 v[8:9], v[4:5], 0, v[106:107]
	global_load_dwordx4 v[82:85], v[6:7], off
	global_load_dwordx4 v[86:89], v[8:9], off
	v_lshl_add_u64 v[4:5], v[4:5], 0, v[108:109]
	global_load_dwordx4 v[90:93], v[2:3], off
	global_load_dwordx4 v[94:97], v[4:5], off
